# mixer: state-pass barrier split into post (after state item) and wait (after attention items); residual epilogue loads hoisted; relaxed first-tile waits in all residual GEMMs
# speedup vs baseline: 1.0165x; 1.0045x over previous
; __global__ void __launch_bounds__(NWAVES * 64, 2) fwd_megakernel(Args args) {
;     ...
;     bool xlmode = (G == 256);
; #pragma unroll
;     for (int x = 0; x < 8; ++x) xlmode = xlmode && (__hip_atomic_load(xl + 64 * x, __ATOMIC_RELAXED, __HIP_MEMORY_SCOPE_AGENT) == 32u);
.LBB0_543:
	s_cmpk_lg_i32 s76, 0x100
	s_mov_b64 s[4:5], 0
	s_cbranch_scc1 .LBB0_552
	s_waitcnt vmcnt(4)
	v_mov_b32_e32 v4, 0
	v_mov_b32_e32 v5, 0xc000
	global_load_dword v6, v4, s[26:27] sc1
	global_load_dword v7, v5, s[74:75] offset:2304 sc1
	global_load_dword v8, v5, s[74:75] offset:2560 sc1
	global_load_dword v9, v5, s[74:75] offset:2816 sc1
	global_load_dword v10, v5, s[74:75] offset:3072 sc1
	global_load_dword v11, v5, s[74:75] offset:3328 sc1
	global_load_dword v12, v5, s[74:75] offset:3584 sc1
	global_load_dword v13, v5, s[74:75] offset:3840 sc1
	s_waitcnt vmcnt(0)
	v_xor_b32_e32 v6, 32, v6
	v_xor_b32_e32 v7, 32, v7
	v_xor_b32_e32 v8, 32, v8
	v_xor_b32_e32 v9, 32, v9
	v_xor_b32_e32 v10, 32, v10
	v_xor_b32_e32 v11, 32, v11
	v_xor_b32_e32 v12, 32, v12
	v_xor_b32_e32 v13, 32, v13
	v_or3_b32 v6, v6, v7, v8
	v_or3_b32 v9, v9, v10, v11
	v_or3_b32 v6, v6, v12, v13
	v_or_b32_e32 v6, v6, v9
	s_nop 0
	v_readfirstlane_b32 s0, v6
	s_nop 3
	s_cmp_eq_u32 s0, 0
	s_cselect_b64 s[4:5], -1, 0

.LBB0_715:
	s_add_u32 s20, s20, 0xb0080
	s_addc_u32 s21, s21, 0
	s_add_u32 s44, s22, 0x100
	v_mov_b32_e32 v0, 0
	s_addc_u32 s45, s23, 0
	s_mov_b32 s47, -2
	s_waitcnt lgkmcnt(0)
	ds_read_b128 v[128:131], v191
	ds_read_b128 v[132:135], v191 offset:1024
	ds_read_b128 v[136:139], v191 offset:2048
	ds_read_b128 v[140:143], v191 offset:3072
	ds_read_b128 v[144:147], v192
	ds_read_b128 v[148:151], v192 offset:1024
	ds_read_b128 v[170:173], v192 offset:2048
	ds_read_b128 v[174:177], v192 offset:3072
	s_add_u32 s22, s20, 0xfff50080
	s_addc_u32 s23, s21, -1
	s_cmp_eq_u32 s47, 40
	s_cselect_b32 s25, s7, s23
	s_cselect_b32 s24, s6, s22
	s_cselect_b32 s23, s19, s45
	s_cselect_b32 s22, s18, s44
	v_lshl_add_u64 v[186:187], s[20:21], 0, v[162:163]
	s_add_i32 m0, s27, 0xc000
	ds_read_b128 v[178:181], v193
	ds_read_b128 v[182:185], v193 offset:1024
	ds_read_b128 v[196:199], v193 offset:2048
	ds_read_b128 v[200:203], v193 offset:3072
	ds_read_b128 v[204:207], v193 offset:4096
	ds_read_b128 v[208:211], v193 offset:5120
	ds_read_b128 v[212:215], v193 offset:6144
	ds_read_b128 v[216:219], v193 offset:7168
	global_load_lds_dwordx4 v[186:187], off
	v_lshl_add_u64 v[186:187], s[20:21], 0, v[164:165]
	s_add_i32 m0, s27, 0xe000
	s_nop 0
	global_load_lds_dwordx4 v[186:187], off
	s_cmp_eq_u32 s101, 1
	s_cbranch_scc1 .Lpk716_r1
	s_waitcnt vmcnt(8)
	s_branch .Lpk716_j1
.Lpk716_r1:
	s_waitcnt vmcnt(32)
.Lpk716_j1:
	s_waitcnt lgkmcnt(0)
	s_barrier
	s_setprio 1
	s_waitcnt lgkmcnt(0)
	v_mfma_f32_16x16x32_bf16 v[124:127], v[128:131], v[178:181], 0
	v_mfma_f32_16x16x32_bf16 v[120:123], v[136:139], v[178:181], 0
	v_mfma_f32_16x16x32_bf16 v[108:111], v[128:131], v[196:199], 0
	v_mfma_f32_16x16x32_bf16 v[104:107], v[136:139], v[196:199], 0
	v_mfma_f32_16x16x32_bf16 v[92:95], v[128:131], v[204:207], 0
	v_mfma_f32_16x16x32_bf16 v[88:91], v[136:139], v[204:207], 0
	v_mfma_f32_16x16x32_bf16 v[76:79], v[128:131], v[212:215], 0
	v_mfma_f32_16x16x32_bf16 v[72:75], v[136:139], v[212:215], 0
	v_mfma_f32_16x16x32_bf16 v[124:127], v[132:135], v[182:185], v[124:127]
	v_mfma_f32_16x16x32_bf16 v[120:123], v[140:143], v[182:185], v[120:123]
	v_mfma_f32_16x16x32_bf16 v[108:111], v[132:135], v[200:203], v[108:111]
	v_mfma_f32_16x16x32_bf16 v[104:107], v[140:143], v[200:203], v[104:107]
	v_mfma_f32_16x16x32_bf16 v[92:95], v[132:135], v[208:211], v[92:95]
	v_mfma_f32_16x16x32_bf16 v[88:91], v[140:143], v[208:211], v[88:91]
	v_mfma_f32_16x16x32_bf16 v[76:79], v[132:135], v[216:219], v[76:79]
	v_mfma_f32_16x16x32_bf16 v[72:75], v[140:143], v[216:219], v[72:75]
	s_setprio 0
	s_setprio 1
	v_mfma_f32_16x16x32_bf16 v[116:119], v[144:147], v[178:181], 0
	v_mfma_f32_16x16x32_bf16 v[112:115], v[170:173], v[178:181], 0
	v_mfma_f32_16x16x32_bf16 v[100:103], v[144:147], v[196:199], 0
	v_mfma_f32_16x16x32_bf16 v[96:99], v[170:173], v[196:199], 0
	v_mfma_f32_16x16x32_bf16 v[84:87], v[144:147], v[204:207], 0
	v_mfma_f32_16x16x32_bf16 v[80:83], v[170:173], v[204:207], 0
	v_mfma_f32_16x16x32_bf16 v[68:71], v[144:147], v[212:215], 0
	v_mfma_f32_16x16x32_bf16 v[64:67], v[170:173], v[212:215], 0
	v_mfma_f32_16x16x32_bf16 v[116:119], v[148:151], v[182:185], v[116:119]
	v_mfma_f32_16x16x32_bf16 v[112:115], v[174:177], v[182:185], v[112:115]
	v_mfma_f32_16x16x32_bf16 v[100:103], v[148:151], v[200:203], v[100:103]
	v_mfma_f32_16x16x32_bf16 v[96:99], v[174:177], v[200:203], v[96:99]
	v_mfma_f32_16x16x32_bf16 v[84:87], v[148:151], v[208:211], v[84:87]
	v_mfma_f32_16x16x32_bf16 v[80:83], v[174:177], v[208:211], v[80:83]
	v_mfma_f32_16x16x32_bf16 v[68:71], v[148:151], v[216:219], v[68:71]
	v_mfma_f32_16x16x32_bf16 v[64:67], v[174:177], v[216:219], v[64:67]
	s_setprio 0
	s_barrier
	s_add_i32 s48, s38, s26
	v_lshl_add_u64 v[186:187], s[22:23], 0, v[156:157]
	s_mov_b32 m0, s48
	ds_read_b128 v[178:181], v193 offset:16384
	ds_read_b128 v[182:185], v193 offset:17408
	global_load_lds_dwordx4 v[186:187], off
	s_add_i32 m0, s48, 0x2000
	s_add_u32 s48, s22, 0xb0000
	v_lshl_add_u64 v[220:221], s[22:23], 0, v[160:161]
	s_addc_u32 s49, s23, 0
	s_add_i32 s50, s39, s26
	ds_read_b128 v[196:199], v193 offset:18432
	ds_read_b128 v[200:203], v193 offset:19456
	global_load_lds_dwordx4 v[220:221], off
	v_lshl_add_u64 v[222:223], s[48:49], 0, v[156:157]
	s_mov_b32 m0, s50
	v_lshl_add_u64 v[224:225], s[24:25], 0, v[158:159]
	ds_read_b128 v[204:207], v193 offset:20480
	global_load_lds_dwordx4 v[222:223], off
	v_lshl_add_u64 v[222:223], s[48:49], 0, v[160:161]
	s_add_i32 m0, s50, 0x2000
	ds_read_b128 v[208:211], v193 offset:21504
	global_load_lds_dwordx4 v[222:223], off
	v_lshl_add_u64 v[222:223], s[24:25], 0, v[154:155]
	s_mov_b32 m0, s27
	ds_read_b128 v[212:215], v193 offset:22528
	global_load_lds_dwordx4 v[222:223], off
	s_mov_b32 m0, s28
	ds_read_b128 v[216:219], v193 offset:23552
	global_load_lds_dwordx4 v[224:225], off
	s_cmp_eq_u32 s101, 1
	s_cbranch_scc1 .Lpk716_r2
	s_waitcnt vmcnt(8)
	s_branch .Lpk716_j2

.Lpk716_j2:
	s_mov_b32 s101, 0
	s_waitcnt lgkmcnt(0)
	s_barrier
	s_setprio 1
	s_waitcnt lgkmcnt(0)
	v_mfma_f32_16x16x32_bf16 v[60:63], v[128:131], v[178:181], 0
	v_mfma_f32_16x16x32_bf16 v[56:59], v[136:139], v[178:181], 0
	v_mfma_f32_16x16x32_bf16 v[44:47], v[128:131], v[196:199], 0
	v_mfma_f32_16x16x32_bf16 v[40:43], v[136:139], v[196:199], 0
	v_mfma_f32_16x16x32_bf16 v[28:31], v[128:131], v[204:207], 0
	v_mfma_f32_16x16x32_bf16 v[24:27], v[136:139], v[204:207], 0
	v_mfma_f32_16x16x32_bf16 v[12:15], v[128:131], v[212:215], 0
	v_mfma_f32_16x16x32_bf16 v[8:11], v[136:139], v[212:215], 0
	v_mfma_f32_16x16x32_bf16 v[60:63], v[132:135], v[182:185], v[60:63]
	v_mfma_f32_16x16x32_bf16 v[56:59], v[140:143], v[182:185], v[56:59]
	v_mfma_f32_16x16x32_bf16 v[44:47], v[132:135], v[200:203], v[44:47]
	v_mfma_f32_16x16x32_bf16 v[40:43], v[140:143], v[200:203], v[40:43]
	v_mfma_f32_16x16x32_bf16 v[28:31], v[132:135], v[208:211], v[28:31]
	v_mfma_f32_16x16x32_bf16 v[24:27], v[140:143], v[208:211], v[24:27]
	v_mfma_f32_16x16x32_bf16 v[12:15], v[132:135], v[216:219], v[12:15]
	v_mfma_f32_16x16x32_bf16 v[8:11], v[140:143], v[216:219], v[8:11]
	s_setprio 0
	s_setprio 1
	v_mfma_f32_16x16x32_bf16 v[52:55], v[144:147], v[178:181], 0
	v_mfma_f32_16x16x32_bf16 v[48:51], v[170:173], v[178:181], 0
	v_mfma_f32_16x16x32_bf16 v[36:39], v[144:147], v[196:199], 0
	v_mfma_f32_16x16x32_bf16 v[32:35], v[170:173], v[196:199], 0
	v_mfma_f32_16x16x32_bf16 v[20:23], v[144:147], v[204:207], 0
	v_mfma_f32_16x16x32_bf16 v[16:19], v[170:173], v[204:207], 0
	v_mfma_f32_16x16x32_bf16 v[4:7], v[144:147], v[212:215], 0
	v_mfma_f32_16x16x32_bf16 v[0:3], v[170:173], v[212:215], 0
	v_mfma_f32_16x16x32_bf16 v[52:55], v[148:151], v[182:185], v[52:55]
	v_mfma_f32_16x16x32_bf16 v[48:51], v[174:177], v[182:185], v[48:51]
	v_mfma_f32_16x16x32_bf16 v[36:39], v[148:151], v[200:203], v[36:39]
	v_mfma_f32_16x16x32_bf16 v[32:35], v[174:177], v[200:203], v[32:35]
	v_mfma_f32_16x16x32_bf16 v[20:23], v[148:151], v[208:211], v[20:23]
	v_mfma_f32_16x16x32_bf16 v[16:19], v[174:177], v[208:211], v[16:19]
	v_mfma_f32_16x16x32_bf16 v[4:7], v[148:151], v[216:219], v[4:7]
	v_mfma_f32_16x16x32_bf16 v[0:3], v[174:177], v[216:219], v[0:3]
	s_setprio 0
	s_barrier
	s_branch .Lpk716_seg3

; __device__ __forceinline__ unsigned cvt_pk_bf16(float lo, float hi) { unsigned r; asm volatile("v_cvt_pk_bf16_f32 %0, %1, %2" : "=v"(r) : "v"(lo), "v"(hi)); return r; }
; __device__ __forceinline__ float bflo(unsigned w) { return __uint_as_float(w << 16); }
; __device__ __forceinline__ float bfhi(unsigned w) { return __uint_as_float(w & 0xffff0000u); }
;     __device__ __forceinline__ void operator()(Acc& acc, const Unit& u, int wr, int wc, int fr, int fq) const { scale(acc, u, wr, wc, fr, fq, PC_GA, true); }
;     __device__ __forceinline__ void operator()(Acc& acc, const Unit& u, int wr, int wc, int fr, int fq) const {
;         const int row0 = u.pm * BM + wr * 64 + fr, col0 = u.pn * BM + wc * 32 + 8 * fq;
; #pragma unroll
;         for (int ai = 0; ai < 2; ++ai) {
;             f32x4 b[4][2][2];
; #pragma unroll
;             for (int m = 0; m < 4; ++m)
; #pragma unroll
;                 for (int bj = 0; bj < 2; ++bj) {
;                     const size_t p = (size_t)(row0 + ai * HALF + m * 16) * DM + col0 + bj * HALF;
;                     if constexpr (BASE_BF16) { const u32x4 w = *(const u32x4*)((const bf16_t*)base + p); b[m][bj][0] = (f32x4){bflo(w.x), bfhi(w.x), bflo(w.y), bfhi(w.y)}; b[m][bj][1] = (f32x4){bflo(w.z), bfhi(w.z), bflo(w.w), bfhi(w.w)}; }
;                     else { b[m][bj][0] = *(const f32x4*)((const float*)base + p); b[m][bj][1] = *(const f32x4*)((const float*)base + p + 4); }
;                 }
; #pragma unroll
;             for (int m = 0; m < 4; ++m) {
;                 const int row = row0 + ai * HALF + m * 16; float sq = 0.f;
; #pragma unroll
;                 for (int bj = 0; bj < 2; ++bj) {
;                     const size_t p = (size_t)row * DM + col0 + bj * HALF;
;                     const f32x4 v0 = b[m][bj][0] + acc[ai][bj][m][0] * scale, v1 = b[m][bj][1] + acc[ai][bj][m][1] * scale;
;                     u32x4 w; w.x = cvt_pk_bf16(v0[0], v0[1]); w.y = cvt_pk_bf16(v0[2], v0[3]); w.z = cvt_pk_bf16(v1[0], v1[1]); w.w = cvt_pk_bf16(v1[2], v1[3]); *(u32x4*)(xb + p) = w;
;                     sq += (v0[0] * v0[0] + v0[1] * v0[1]) + (v0[2] * v0[2] + v0[3] * v0[3]) + (v1[0] * v1[0] + v1[1] * v1[1]) + (v1[2] * v1[2] + v1[3] * v1[3]);
;                 }
;                 sq += __shfl_xor(sq, 16); sq += __shfl_xor(sq, 32);
;                 if (fq == 0) atomicAdd(ss + row, sq);
;             }
.LBB0_719:
	v_lshl_or_b32 v170, s43, 8, v190
	v_lshl_add_u32 v174, s42, 8, v188
	v_ashrrev_i32_e32 v171, 31, v170
	v_lshlrev_b64 v[204:205], 1, v[170:171]
	v_ashrrev_i32_e32 v175, 31, v174
	v_lshl_add_u64 v[172:173], s[12:13], 0, v[204:205]
	v_lshlrev_b64 v[206:207], 11, v[174:175]
	v_lshl_add_u64 v[128:129], v[172:173], 0, v[206:207]
	global_load_dwordx4 v[196:199], v[128:129], off
	global_load_dwordx4 v[200:203], v[128:129], off offset:256
	v_or_b32_e32 v184, 16, v174
	v_or_b32_e32 v180, 32, v174
	v_or_b32_e32 v176, 48, v174
	v_ashrrev_i32_e32 v185, 31, v184
	v_ashrrev_i32_e32 v181, 31, v180
	v_ashrrev_i32_e32 v177, 31, v176
	v_lshlrev_b64 v[186:187], 11, v[184:185]
	v_lshlrev_b64 v[182:183], 11, v[180:181]
	v_lshlrev_b64 v[178:179], 11, v[176:177]
	v_lshl_add_u64 v[128:129], v[172:173], 0, v[186:187]
	v_lshl_add_u64 v[130:131], v[172:173], 0, v[182:183]
	v_lshl_add_u64 v[208:209], v[172:173], 0, v[178:179]
	global_load_dwordx4 v[148:151], v[128:129], off
	global_load_dwordx4 v[144:147], v[128:129], off offset:256
	global_load_dwordx4 v[140:143], v[130:131], off
	global_load_dwordx4 v[136:139], v[130:131], off offset:256
	global_load_dwordx4 v[132:135], v[208:209], off
	s_nop 0
	global_load_dwordx4 v[128:131], v[208:209], off offset:256
	v_add_u32_e32 v250, 0x80, v174
	v_ashrrev_i32_e32 v251, 31, v250
	v_lshlrev_b64 v[252:253], 11, v[250:251]
	v_lshl_add_u64 v[254:255], v[172:173], 0, v[252:253]
	global_load_dwordx4 v[216:219], v[254:255], off
	global_load_dwordx4 v[220:223], v[254:255], off offset:256
	v_add_u32_e32 v250, 0x90, v174
	v_ashrrev_i32_e32 v251, 31, v250
	v_lshlrev_b64 v[252:253], 11, v[250:251]
	v_lshl_add_u64 v[254:255], v[172:173], 0, v[252:253]
	global_load_dwordx4 v[224:227], v[254:255], off
	global_load_dwordx4 v[228:231], v[254:255], off offset:256
	v_add_u32_e32 v250, 0xa0, v174
	v_ashrrev_i32_e32 v251, 31, v250
	v_lshlrev_b64 v[252:253], 11, v[250:251]
	v_lshl_add_u64 v[254:255], v[172:173], 0, v[252:253]
	global_load_dwordx4 v[232:235], v[254:255], off
	global_load_dwordx4 v[236:239], v[254:255], off offset:256
	v_add_u32_e32 v250, 0xb0, v174
	v_ashrrev_i32_e32 v251, 31, v250
	v_lshlrev_b64 v[252:253], 11, v[250:251]
	v_lshl_add_u64 v[254:255], v[172:173], 0, v[252:253]
	global_load_dwordx4 v[240:243], v[254:255], off
	global_load_dwordx4 v[246:249], v[254:255], off offset:256
	v_and_b32_e32 v208, 64, v194
	v_xor_b32_e32 v195, 16, v194
	v_add_u32_e32 v208, 64, v208
	v_xor_b32_e32 v209, 32, v194
	v_cmp_lt_i32_e32 vcc, v195, v208
	v_lshl_add_u64 v[206:207], s[12:13], 0, v[206:207]
	v_lshl_add_u64 v[204:205], v[206:207], 0, v[204:205]
	v_cndmask_b32_e32 v195, v194, v195, vcc
	v_cmp_lt_i32_e32 vcc, v209, v208
	v_lshlrev_b32_e32 v195, 2, v195
	s_waitcnt vmcnt(0)
	v_lshlrev_b32_e32 v206, 16, v196
	v_and_b32_e32 v207, 0xffff0000, v196
	v_lshlrev_b32_e32 v196, 16, v197
	v_and_b32_e32 v197, 0xffff0000, v197
	v_lshlrev_b32_e32 v210, 16, v200
	v_and_b32_e32 v211, 0xffff0000, v200
	v_lshlrev_b32_e32 v200, 16, v201
	v_and_b32_e32 v201, 0xffff0000, v201
	v_cndmask_b32_e32 v214, v194, v209, vcc
	v_lshlrev_b32_e32 v208, 16, v198
	v_and_b32_e32 v209, 0xffff0000, v198
	v_lshlrev_b32_e32 v198, 16, v199
	v_and_b32_e32 v199, 0xffff0000, v199
	v_lshlrev_b32_e32 v212, 16, v202
	v_and_b32_e32 v213, 0xffff0000, v202
	v_lshlrev_b32_e32 v202, 16, v203
	v_and_b32_e32 v203, 0xffff0000, v203
	v_pk_fma_f32 v[126:127], v[126:127], 0.5, v[196:197] op_sel_hi:[1,0,1]
	v_pk_fma_f32 v[124:125], v[124:125], 0.5, v[206:207] op_sel_hi:[1,0,1]
	v_pk_fma_f32 v[118:119], v[118:119], 0.5, v[200:201] op_sel_hi:[1,0,1]
	v_pk_fma_f32 v[116:117], v[116:117], 0.5, v[210:211] op_sel_hi:[1,0,1]
	v_pk_fma_f32 v[122:123], v[122:123], 0.5, v[198:199] op_sel_hi:[1,0,1]
	v_pk_fma_f32 v[120:121], v[120:121], 0.5, v[208:209] op_sel_hi:[1,0,1]
	v_pk_fma_f32 v[196:197], v[114:115], 0.5, v[202:203] op_sel_hi:[1,0,1]
	v_pk_fma_f32 v[198:199], v[112:113], 0.5, v[212:213] op_sel_hi:[1,0,1]
	v_mul_f32_e32 v114, v125, v125
	v_mul_f32_e32 v115, v127, v127
	v_mul_f32_e32 v200, v117, v117
	v_mul_f32_e32 v201, v119, v119
	v_cvt_pk_bf16_f32 v112, v124, v125
	v_mul_f32_e32 v125, v121, v121
	v_mul_f32_e32 v202, v199, v199
	v_fmac_f32_e32 v114, v124, v124
	v_fmac_f32_e32 v115, v126, v126
	v_fmac_f32_e32 v200, v116, v116
	v_fmac_f32_e32 v201, v118, v118
	v_cvt_pk_bf16_f32 v113, v126, v127
	v_mul_f32_e32 v127, v123, v123
	v_mul_f32_e32 v203, v197, v197
	v_fmac_f32_e32 v125, v120, v120
	v_fmac_f32_e32 v202, v198, v198
	v_add_f32_e32 v114, v114, v115
	v_add_f32_e32 v115, v200, v201
	v_fmac_f32_e32 v127, v122, v122
	v_fmac_f32_e32 v203, v196, v196
	v_add_f32_e32 v114, v125, v114
	v_add_f32_e32 v115, v202, v115
	v_add_f32_e32 v114, v127, v114
	v_add_f32_e32 v115, v203, v115
	v_add_f32_e32 v124, v114, v115
	ds_bpermute_b32 v125, v195, v124
	v_cvt_pk_bf16_f32 v114, v120, v121
	v_cvt_pk_bf16_f32 v115, v122, v123
	global_store_dwordx4 v[204:205], v[112:115], off
	v_cvt_pk_bf16_f32 v116, v116, v117
	v_cvt_pk_bf16_f32 v117, v118, v119
	v_cvt_pk_bf16_f32 v118, v198, v199
	v_cvt_pk_bf16_f32 v119, v196, v197
	global_store_dwordx4 v[204:205], v[116:119], off offset:256
	s_waitcnt lgkmcnt(0)
	v_add_f32_e32 v113, v124, v125
	v_lshlrev_b32_e32 v112, 2, v214
	ds_bpermute_b32 v114, v112, v113
	s_and_saveexec_b64 s[20:21], s[2:3]
	s_cbranch_execz .LBB0_721
	v_lshl_add_u64 v[116:117], v[174:175], 2, s[8:9]
	s_waitcnt lgkmcnt(0)
	v_add_f32_e32 v113, v113, v114
	global_atomic_add_f32 v[116:117], v113, off

; __device__ __forceinline__ unsigned cvt_pk_bf16(float lo, float hi) { unsigned r; asm volatile("v_cvt_pk_bf16_f32 %0, %1, %2" : "=v"(r) : "v"(lo), "v"(hi)); return r; }
;     __device__ __forceinline__ void operator()(Acc& acc, const Unit& u, int wr, int wc, int fr, int fq) const {
;     ...
;             for (int m = 0; m < 4; ++m) {
;                 const int row = row0 + ai * HALF + m * 16; float sq = 0.f;
; #pragma unroll
;                 for (int bj = 0; bj < 2; ++bj) {
;                     const size_t p = (size_t)row * DM + col0 + bj * HALF;
;                     const f32x4 v0 = b[m][bj][0] + acc[ai][bj][m][0] * scale, v1 = b[m][bj][1] + acc[ai][bj][m][1] * scale;
;                     u32x4 w; w.x = cvt_pk_bf16(v0[0], v0[1]); w.y = cvt_pk_bf16(v0[2], v0[3]); w.z = cvt_pk_bf16(v1[0], v1[1]); w.w = cvt_pk_bf16(v1[2], v1[3]); *(u32x4*)(xb + p) = w;
;                     sq += (v0[0] * v0[0] + v0[1] * v0[1]) + (v0[2] * v0[2] + v0[3] * v0[3]) + (v1[0] * v1[0] + v1[1] * v1[1]) + (v1[2] * v1[2] + v1[3] * v1[3]);
;                 }
;                 sq += __shfl_xor(sq, 16); sq += __shfl_xor(sq, 32);
;                 if (fq == 0) atomicAdd(ss + row, sq);
;             }
.LBB0_727:
	s_or_b64 exec, exec, s[20:21]
	v_add_u32_e32 v100, 0x80, v174
	v_ashrrev_i32_e32 v101, 31, v100
	v_lshlrev_b64 v[110:111], 11, v[100:101]
	s_waitcnt lgkmcnt(0)
	v_lshl_add_u64 v[64:65], v[172:173], 0, v[110:111]
	v_add_u32_e32 v96, 0x90, v174
	v_add_u32_e32 v92, 0xa0, v174
	v_add_u32_e32 v88, 0xb0, v174
	v_ashrrev_i32_e32 v97, 31, v96
	v_ashrrev_i32_e32 v93, 31, v92
	v_ashrrev_i32_e32 v89, 31, v88
	v_lshlrev_b64 v[98:99], 11, v[96:97]
	v_lshlrev_b64 v[94:95], 11, v[92:93]
	v_lshlrev_b64 v[90:91], 11, v[88:89]
	v_lshl_add_u64 v[64:65], v[172:173], 0, v[98:99]
	v_lshl_add_u64 v[66:67], v[172:173], 0, v[94:95]
	v_lshl_add_u64 v[114:115], v[172:173], 0, v[90:91]
	v_mov_b32_e32 v102, v216
	v_mov_b32_e32 v103, v217
	v_mov_b32_e32 v104, v218
	v_mov_b32_e32 v105, v219
	v_mov_b32_e32 v106, v220
	v_mov_b32_e32 v107, v221
	v_mov_b32_e32 v108, v222
	v_mov_b32_e32 v109, v223
	v_mov_b32_e32 v84, v224
	v_mov_b32_e32 v85, v225
	v_mov_b32_e32 v86, v226
	v_mov_b32_e32 v87, v227
	v_mov_b32_e32 v80, v228
	v_mov_b32_e32 v81, v229
	v_mov_b32_e32 v82, v230
	v_mov_b32_e32 v83, v231
	v_mov_b32_e32 v76, v232
	v_mov_b32_e32 v77, v233
	v_mov_b32_e32 v78, v234
	v_mov_b32_e32 v79, v235
	v_mov_b32_e32 v72, v236
	v_mov_b32_e32 v73, v237
	v_mov_b32_e32 v74, v238
	v_mov_b32_e32 v75, v239
	v_mov_b32_e32 v68, v240
	v_mov_b32_e32 v69, v241
	v_mov_b32_e32 v70, v242
	v_mov_b32_e32 v71, v243
	v_mov_b32_e32 v64, v246
	v_mov_b32_e32 v65, v247
	v_mov_b32_e32 v66, v248
	v_mov_b32_e32 v67, v249
	v_lshlrev_b32_e32 v114, 16, v102
	v_and_b32_e32 v115, 0xffff0000, v102
	v_lshlrev_b32_e32 v102, 16, v103
	v_and_b32_e32 v103, 0xffff0000, v103
	v_lshlrev_b32_e32 v118, 16, v106
	v_and_b32_e32 v119, 0xffff0000, v106
	v_lshlrev_b32_e32 v106, 16, v107
	v_and_b32_e32 v107, 0xffff0000, v107
	v_lshlrev_b32_e32 v116, 16, v104
	v_and_b32_e32 v117, 0xffff0000, v104
	v_lshlrev_b32_e32 v104, 16, v105
	v_and_b32_e32 v105, 0xffff0000, v105
	v_lshlrev_b32_e32 v120, 16, v108
	v_and_b32_e32 v121, 0xffff0000, v108
	v_pk_fma_f32 v[62:63], v[62:63], 0.5, v[102:103] op_sel_hi:[1,0,1]
	v_pk_fma_f32 v[60:61], v[60:61], 0.5, v[114:115] op_sel_hi:[1,0,1]
	v_pk_fma_f32 v[54:55], v[54:55], 0.5, v[106:107] op_sel_hi:[1,0,1]
	v_pk_fma_f32 v[52:53], v[52:53], 0.5, v[118:119] op_sel_hi:[1,0,1]
	v_lshlrev_b32_e32 v108, 16, v109
	v_and_b32_e32 v109, 0xffff0000, v109
	v_pk_fma_f32 v[58:59], v[58:59], 0.5, v[104:105] op_sel_hi:[1,0,1]
	v_pk_fma_f32 v[56:57], v[56:57], 0.5, v[116:117] op_sel_hi:[1,0,1]
	v_pk_fma_f32 v[104:105], v[48:49], 0.5, v[120:121] op_sel_hi:[1,0,1]
	v_cvt_pk_bf16_f32 v48, v60, v61
	v_cvt_pk_bf16_f32 v49, v62, v63
	v_mul_f32_e32 v61, v61, v61
	v_mul_f32_e32 v63, v63, v63
	v_mul_f32_e32 v106, v53, v53
	v_mul_f32_e32 v107, v55, v55
	v_pk_fma_f32 v[102:103], v[50:51], 0.5, v[108:109] op_sel_hi:[1,0,1]
	v_cvt_pk_bf16_f32 v50, v56, v57
	v_cvt_pk_bf16_f32 v51, v58, v59
	v_mul_f32_e32 v57, v57, v57
	v_mul_f32_e32 v59, v59, v59
	v_mul_f32_e32 v108, v105, v105
	v_fmac_f32_e32 v61, v60, v60
	v_fmac_f32_e32 v63, v62, v62
	v_fmac_f32_e32 v106, v52, v52
	v_fmac_f32_e32 v107, v54, v54
	v_mul_f32_e32 v109, v103, v103
	v_fmac_f32_e32 v57, v56, v56
	v_fmac_f32_e32 v59, v58, v58
	v_fmac_f32_e32 v108, v104, v104
	v_add_f32_e32 v56, v61, v63
	v_add_f32_e32 v58, v106, v107
	v_fmac_f32_e32 v109, v102, v102
	v_add_f32_e32 v56, v57, v56
	v_add_f32_e32 v57, v108, v58
	v_add_f32_e32 v56, v59, v56
	v_add_f32_e32 v57, v109, v57
	v_add_f32_e32 v58, v56, v57
	ds_bpermute_b32 v59, v195, v58
	v_lshl_add_u64 v[56:57], s[12:13], 0, v[110:111]
	v_lshl_add_u64 v[56:57], v[170:171], 1, v[56:57]
	global_store_dwordx4 v[56:57], v[48:51], off
	s_waitcnt lgkmcnt(0)
	s_nop 0
	v_add_f32_e32 v48, v58, v59
	ds_bpermute_b32 v49, v112, v48
	v_cvt_pk_bf16_f32 v50, v52, v53
	v_cvt_pk_bf16_f32 v51, v54, v55
	v_cvt_pk_bf16_f32 v52, v104, v105
	v_cvt_pk_bf16_f32 v53, v102, v103
	global_store_dwordx4 v[56:57], v[50:53], off offset:256
	s_and_saveexec_b64 s[20:21], s[2:3]
	s_cbranch_execz .LBB0_729
	v_lshl_add_u64 v[50:51], v[100:101], 2, s[8:9]
	s_waitcnt lgkmcnt(0)
	v_add_f32_e32 v48, v48, v49
	global_atomic_add_f32 v[50:51], v48, off
.LBB0_729:
	s_or_b64 exec, exec, s[20:21]
	v_lshlrev_b32_e32 v48, 16, v84
	s_waitcnt lgkmcnt(0)
	v_and_b32_e32 v49, 0xffff0000, v84
	v_lshlrev_b32_e32 v50, 16, v85
	v_and_b32_e32 v51, 0xffff0000, v85
	v_lshlrev_b32_e32 v52, 16, v86
	v_and_b32_e32 v53, 0xffff0000, v86
	v_pk_fma_f32 v[44:45], v[44:45], 0.5, v[48:49] op_sel_hi:[1,0,1]
	v_pk_fma_f32 v[46:47], v[46:47], 0.5, v[50:51] op_sel_hi:[1,0,1]
	v_pk_fma_f32 v[50:51], v[40:41], 0.5, v[52:53] op_sel_hi:[1,0,1]
	v_cvt_pk_bf16_f32 v40, v44, v45
	v_mul_f32_e32 v45, v45, v45
	v_fmac_f32_e32 v45, v44, v44
	v_mul_f32_e32 v44, v47, v47
	v_lshlrev_b32_e32 v56, 16, v80
	v_and_b32_e32 v57, 0xffff0000, v80
	v_lshlrev_b32_e32 v58, 16, v81
	v_and_b32_e32 v59, 0xffff0000, v81
	v_fmac_f32_e32 v44, v46, v46
	v_lshlrev_b32_e32 v54, 16, v87
	v_and_b32_e32 v55, 0xffff0000, v87
	v_lshlrev_b32_e32 v60, 16, v82
	v_and_b32_e32 v61, 0xffff0000, v82
	v_add_f32_e32 v44, v45, v44
	v_mul_f32_e32 v45, v51, v51
	v_pk_fma_f32 v[38:39], v[38:39], 0.5, v[58:59] op_sel_hi:[1,0,1]
	v_pk_fma_f32 v[36:37], v[36:37], 0.5, v[56:57] op_sel_hi:[1,0,1]
	v_pk_fma_f32 v[48:49], v[42:43], 0.5, v[54:55] op_sel_hi:[1,0,1]
	v_cvt_pk_bf16_f32 v41, v46, v47
	v_fmac_f32_e32 v45, v50, v50
	v_pk_fma_f32 v[46:47], v[32:33], 0.5, v[60:61] op_sel_hi:[1,0,1]
	v_mul_f32_e32 v32, v37, v37
	v_mul_f32_e32 v33, v39, v39
	v_add_f32_e32 v44, v45, v44
	v_mul_f32_e32 v45, v49, v49
	v_fmac_f32_e32 v32, v36, v36
	v_fmac_f32_e32 v33, v38, v38
	v_lshlrev_b32_e32 v62, 16, v83
	v_and_b32_e32 v63, 0xffff0000, v83
	v_fmac_f32_e32 v45, v48, v48
	v_add_f32_e32 v32, v32, v33
	v_mul_f32_e32 v33, v47, v47
	v_cvt_pk_bf16_f32 v42, v50, v51
	v_cvt_pk_bf16_f32 v43, v48, v49
	v_add_f32_e32 v48, v45, v44
	v_pk_fma_f32 v[44:45], v[34:35], 0.5, v[62:63] op_sel_hi:[1,0,1]
	v_fmac_f32_e32 v33, v46, v46
	v_add_f32_e32 v32, v33, v32
	v_mul_f32_e32 v33, v45, v45
	v_fmac_f32_e32 v33, v44, v44
	v_add_f32_e32 v32, v33, v32
	v_add_f32_e32 v35, v48, v32
	ds_bpermute_b32 v50, v195, v35
	v_lshl_add_u64 v[32:33], s[12:13], 0, v[98:99]
	v_lshl_add_u64 v[48:49], v[170:171], 1, v[32:33]
	global_store_dwordx4 v[48:49], v[40:43], off
	v_cvt_pk_bf16_f32 v34, v36, v37
	s_waitcnt lgkmcnt(0)
	v_add_f32_e32 v32, v35, v50
	ds_bpermute_b32 v33, v112, v32
	v_cvt_pk_bf16_f32 v35, v38, v39
	v_cvt_pk_bf16_f32 v36, v46, v47
	v_cvt_pk_bf16_f32 v37, v44, v45
	global_store_dwordx4 v[48:49], v[34:37], off offset:256
	s_and_saveexec_b64 s[20:21], s[2:3]
	s_cbranch_execz .LBB0_731
	v_lshl_add_u64 v[34:35], v[96:97], 2, s[8:9]
	s_waitcnt lgkmcnt(0)
	v_add_f32_e32 v32, v32, v33
	global_atomic_add_f32 v[34:35], v32, off
; __device__ __forceinline__ unsigned cvt_pk_bf16(float lo, float hi) { unsigned r; asm volatile("v_cvt_pk_bf16_f32 %0, %1, %2" : "=v"(r) : "v"(lo), "v"(hi)); return r; }
; #define PG8_WAIT_V(n) asm volatile("s_waitcnt vmcnt(" #n ")" ::: "memory")
; #define PG8_BAR __builtin_amdgcn_s_barrier()
;     __device__ __forceinline__ void operator()(Acc& acc, const Unit& u, int wr, int wc, int fr, int fq) const {
;     ...
;             for (int m = 0; m < 4; ++m) {
;                 const int row = row0 + ai * HALF + m * 16; float sq = 0.f;
; #pragma unroll
;                 for (int bj = 0; bj < 2; ++bj) {
;                     const size_t p = (size_t)row * DM + col0 + bj * HALF;
;                     const f32x4 v0 = b[m][bj][0] + acc[ai][bj][m][0] * scale, v1 = b[m][bj][1] + acc[ai][bj][m][1] * scale;
;                     u32x4 w; w.x = cvt_pk_bf16(v0[0], v0[1]); w.y = cvt_pk_bf16(v0[2], v0[3]); w.z = cvt_pk_bf16(v1[0], v1[1]); w.w = cvt_pk_bf16(v1[2], v1[3]); *(u32x4*)(xb + p) = w;
;                     sq += (v0[0] * v0[0] + v0[1] * v0[1]) + (v0[2] * v0[2] + v0[3] * v0[3]) + (v1[0] * v1[0] + v1[1] * v1[1]) + (v1[2] * v1[2] + v1[3] * v1[3]);
;                 }
;                 sq += __shfl_xor(sq, 16); sq += __shfl_xor(sq, 32);
;                 if (fq == 0) atomicAdd(ss + row, sq);
;             }
; template <class Epi, class Sched, bool ALIGN_EPI>
; __device__ __forceinline__ void gemm_phase(LAS unsigned char* lds, const Gemm g, const Sched& S, const Epi& E) {
;     ...
;         cur = nxt; cA = nA; cB = nB; ++ui;
;         if constexpr (ALIGN_EPI) { if (wr == 1) PG8_BAR; }
;     }
;     PG8_WAIT_V(0);
;     if constexpr (!ALIGN_EPI) { if (wr == 0) PG8_BAR; }
;     PG8_BAR;
.LBB0_731:
	s_or_b64 exec, exec, s[20:21]
	v_lshlrev_b32_e32 v32, 16, v76
	s_waitcnt lgkmcnt(0)
	v_and_b32_e32 v33, 0xffff0000, v76
	v_lshlrev_b32_e32 v34, 16, v77
	v_and_b32_e32 v35, 0xffff0000, v77
	v_lshlrev_b32_e32 v36, 16, v78
	v_and_b32_e32 v37, 0xffff0000, v78
	v_pk_fma_f32 v[28:29], v[28:29], 0.5, v[32:33] op_sel_hi:[1,0,1]
	v_pk_fma_f32 v[30:31], v[30:31], 0.5, v[34:35] op_sel_hi:[1,0,1]
	v_pk_fma_f32 v[34:35], v[24:25], 0.5, v[36:37] op_sel_hi:[1,0,1]
	v_cvt_pk_bf16_f32 v24, v28, v29
	v_mul_f32_e32 v29, v29, v29
	v_fmac_f32_e32 v29, v28, v28
	v_mul_f32_e32 v28, v31, v31
	v_lshlrev_b32_e32 v40, 16, v72
	v_and_b32_e32 v41, 0xffff0000, v72
	v_lshlrev_b32_e32 v42, 16, v73
	v_and_b32_e32 v43, 0xffff0000, v73
	v_fmac_f32_e32 v28, v30, v30
	v_lshlrev_b32_e32 v38, 16, v79
	v_and_b32_e32 v39, 0xffff0000, v79
	v_lshlrev_b32_e32 v44, 16, v74
	v_and_b32_e32 v45, 0xffff0000, v74
	v_add_f32_e32 v28, v29, v28
	v_mul_f32_e32 v29, v35, v35
	v_pk_fma_f32 v[22:23], v[22:23], 0.5, v[42:43] op_sel_hi:[1,0,1]
	v_pk_fma_f32 v[20:21], v[20:21], 0.5, v[40:41] op_sel_hi:[1,0,1]
	v_pk_fma_f32 v[32:33], v[26:27], 0.5, v[38:39] op_sel_hi:[1,0,1]
	v_cvt_pk_bf16_f32 v25, v30, v31
	v_fmac_f32_e32 v29, v34, v34
	v_pk_fma_f32 v[30:31], v[16:17], 0.5, v[44:45] op_sel_hi:[1,0,1]
	v_mul_f32_e32 v16, v21, v21
	v_mul_f32_e32 v17, v23, v23
	v_add_f32_e32 v28, v29, v28
	v_mul_f32_e32 v29, v33, v33
	v_fmac_f32_e32 v16, v20, v20
	v_fmac_f32_e32 v17, v22, v22
	v_lshlrev_b32_e32 v46, 16, v75
	v_and_b32_e32 v47, 0xffff0000, v75
	v_fmac_f32_e32 v29, v32, v32
	v_add_f32_e32 v16, v16, v17
	v_mul_f32_e32 v17, v31, v31
	v_cvt_pk_bf16_f32 v26, v34, v35
	v_cvt_pk_bf16_f32 v27, v32, v33
	v_add_f32_e32 v32, v29, v28
	v_pk_fma_f32 v[28:29], v[18:19], 0.5, v[46:47] op_sel_hi:[1,0,1]
	v_fmac_f32_e32 v17, v30, v30
	v_add_f32_e32 v16, v17, v16
	v_mul_f32_e32 v17, v29, v29
	v_fmac_f32_e32 v17, v28, v28
	v_add_f32_e32 v16, v17, v16
	v_add_f32_e32 v19, v32, v16
	ds_bpermute_b32 v34, v195, v19
	v_lshl_add_u64 v[16:17], s[12:13], 0, v[94:95]
	v_lshl_add_u64 v[32:33], v[170:171], 1, v[16:17]
	global_store_dwordx4 v[32:33], v[24:27], off
	v_cvt_pk_bf16_f32 v18, v20, v21
	s_waitcnt lgkmcnt(0)
	v_add_f32_e32 v16, v19, v34
	ds_bpermute_b32 v17, v112, v16
	v_cvt_pk_bf16_f32 v19, v22, v23
	v_cvt_pk_bf16_f32 v20, v30, v31
	v_cvt_pk_bf16_f32 v21, v28, v29
	global_store_dwordx4 v[32:33], v[18:21], off offset:256
	s_and_saveexec_b64 s[20:21], s[2:3]
	s_cbranch_execz .LBB0_733
	v_lshl_add_u64 v[18:19], v[92:93], 2, s[8:9]
	s_waitcnt lgkmcnt(0)
	v_add_f32_e32 v16, v16, v17
	global_atomic_add_f32 v[18:19], v16, off
.LBB0_733:
	s_or_b64 exec, exec, s[20:21]
	v_lshlrev_b32_e32 v16, 16, v68
	s_waitcnt lgkmcnt(0)
	v_and_b32_e32 v17, 0xffff0000, v68
	v_lshlrev_b32_e32 v18, 16, v69
	v_and_b32_e32 v19, 0xffff0000, v69
	v_lshlrev_b32_e32 v20, 16, v70
	v_and_b32_e32 v21, 0xffff0000, v70
	v_pk_fma_f32 v[12:13], v[12:13], 0.5, v[16:17] op_sel_hi:[1,0,1]
	v_pk_fma_f32 v[14:15], v[14:15], 0.5, v[18:19] op_sel_hi:[1,0,1]
	v_pk_fma_f32 v[18:19], v[8:9], 0.5, v[20:21] op_sel_hi:[1,0,1]
	v_cvt_pk_bf16_f32 v8, v12, v13
	v_mul_f32_e32 v13, v13, v13
	v_fmac_f32_e32 v13, v12, v12
	v_mul_f32_e32 v12, v15, v15
	v_lshlrev_b32_e32 v24, 16, v64
	v_and_b32_e32 v25, 0xffff0000, v64
	v_lshlrev_b32_e32 v26, 16, v65
	v_and_b32_e32 v27, 0xffff0000, v65
	v_fmac_f32_e32 v12, v14, v14
	v_lshlrev_b32_e32 v22, 16, v71
	v_and_b32_e32 v23, 0xffff0000, v71
	v_lshlrev_b32_e32 v28, 16, v66
	v_and_b32_e32 v29, 0xffff0000, v66
	v_add_f32_e32 v12, v13, v12
	v_mul_f32_e32 v13, v19, v19
	v_pk_fma_f32 v[6:7], v[6:7], 0.5, v[26:27] op_sel_hi:[1,0,1]
	v_pk_fma_f32 v[4:5], v[4:5], 0.5, v[24:25] op_sel_hi:[1,0,1]
	v_pk_fma_f32 v[16:17], v[10:11], 0.5, v[22:23] op_sel_hi:[1,0,1]
	v_cvt_pk_bf16_f32 v9, v14, v15
	v_fmac_f32_e32 v13, v18, v18
	v_pk_fma_f32 v[14:15], v[0:1], 0.5, v[28:29] op_sel_hi:[1,0,1]
	v_mul_f32_e32 v0, v5, v5
	v_mul_f32_e32 v1, v7, v7
	v_add_f32_e32 v12, v13, v12
	v_mul_f32_e32 v13, v17, v17
	v_fmac_f32_e32 v0, v4, v4
	v_fmac_f32_e32 v1, v6, v6
	v_lshlrev_b32_e32 v30, 16, v67
	v_and_b32_e32 v31, 0xffff0000, v67
	v_fmac_f32_e32 v13, v16, v16
	v_add_f32_e32 v0, v0, v1
	v_mul_f32_e32 v1, v15, v15
	v_cvt_pk_bf16_f32 v10, v18, v19
	v_cvt_pk_bf16_f32 v11, v16, v17
	v_add_f32_e32 v16, v13, v12
	v_pk_fma_f32 v[12:13], v[2:3], 0.5, v[30:31] op_sel_hi:[1,0,1]
	v_fmac_f32_e32 v1, v14, v14
	v_add_f32_e32 v0, v1, v0
	v_mul_f32_e32 v1, v13, v13
	v_fmac_f32_e32 v1, v12, v12
	v_add_f32_e32 v0, v1, v0
	v_add_f32_e32 v3, v16, v0
	ds_bpermute_b32 v18, v195, v3
	v_lshl_add_u64 v[0:1], s[12:13], 0, v[90:91]
	v_lshl_add_u64 v[16:17], v[170:171], 1, v[0:1]
	global_store_dwordx4 v[16:17], v[8:11], off
	v_cvt_pk_bf16_f32 v2, v4, v5
	s_waitcnt lgkmcnt(0)
	v_add_f32_e32 v0, v3, v18
	ds_bpermute_b32 v1, v112, v0
	v_cvt_pk_bf16_f32 v3, v6, v7
	v_cvt_pk_bf16_f32 v4, v14, v15
	v_cvt_pk_bf16_f32 v5, v12, v13
	global_store_dwordx4 v[16:17], v[2:5], off offset:256
	s_and_saveexec_b64 s[20:21], s[2:3]
	s_cbranch_execz .LBB0_735
	v_lshl_add_u64 v[2:3], v[88:89], 2, s[8:9]
	s_waitcnt lgkmcnt(0)
	v_add_f32_e32 v0, v0, v1
	global_atomic_add_f32 v[2:3], v0, off
.LBB0_735:
	s_or_b64 exec, exec, s[20:21]
	s_and_b64 vcc, exec, s[4:5]
	s_mov_b64 s[4:5], -1
	s_mov_b32 s101, 1
	s_cbranch_vccnz .LBB0_704
	s_andn2_b64 vcc, exec, s[10:11]
	s_cbranch_vccnz .LBB0_703
	s_barrier
	s_branch .LBB0_703
.LBB0_738:
	s_mov_b32 s101, 0
	s_waitcnt vmcnt(0)
	s_barrier
.LBB0_739:
	v_readlane_b32 s0, v245, 11
	v_readlane_b32 s1, v245, 12
	s_mov_b64 s[2:3], -1
	s_and_b64 vcc, exec, s[0:1]
	s_cbranch_vccz .LBB0_793
	s_waitcnt vmcnt(0)
	s_waitcnt vmcnt(0) lgkmcnt(0)
	s_barrier
	s_and_saveexec_b64 s[2:3], s[90:91]
	s_cbranch_execz .LBB0_792
	s_add_i32 s0, 0, 0x23fc0
	v_mov_b32_e32 v0, s0
	s_waitcnt vmcnt(0) expcnt(0) lgkmcnt(0)
	ds_read_b32 v2, v0
	s_add_i32 s0, 0, 0x23fc4
	v_mov_b32_e32 v0, s0
	ds_read_b32 v0, v0
	s_waitcnt lgkmcnt(1)
	v_cmp_ne_u32_e32 vcc, 0, v2
	s_cbranch_vccnz .LBB0_756
	s_add_u32 s4, s74, 0x1000
	s_addc_u32 s5, s75, 0
	s_add_u32 s6, s74, 0x1100
	s_addc_u32 s7, s75, 0
	s_add_u32 s10, s74, 0x1200
	s_addc_u32 s11, s75, 0
	s_mul_i32 s0, s77, s94
	s_add_u32 s12, s74, 0x1300
	s_mul_i32 s0, s0, s76
	s_addc_u32 s13, s75, 0
	s_mov_b32 s1, 1
	v_mov_b32_e32 v16, 0
	s_branch .LBB0_744

; __device__ __forceinline__ unsigned xb_ld(unsigned* p)              { return __hip_atomic_load(p, __ATOMIC_RELAXED, __HIP_MEMORY_SCOPE_AGENT); }
; __device__ __forceinline__ unsigned xb_add(unsigned* p, unsigned v) { return __hip_atomic_fetch_add(p, v, __ATOMIC_RELAXED, __HIP_MEMORY_SCOPE_AGENT); }
; __device__ __forceinline__ void xcd_local_barrier(unsigned* xl, unsigned x) {
;     asm volatile("s_waitcnt vmcnt(0)" ::: "memory");
;     __syncthreads();
;     if (threadIdx.x == 0) {
;         __builtin_amdgcn_s_waitcnt(0);
;         unsigned* sub = xl + 512 + 64 * x; unsigned* gen = xl + 1024 + 64 * x;
;         const unsigned old = xb_add(sub, 1u), g = old / 32u;
;         if (old + 1u == (g + 1u) * 32u) (void)xb_add(gen, 1u);
;         else { unsigned sp = 0; while (xb_ld(gen) == g) { __builtin_amdgcn_s_sleep(1); if (++sp > (1u << 22)) break; } }
.LBB0_1086:
	s_waitcnt vmcnt(0) lgkmcnt(0)
	s_barrier
	s_and_saveexec_b64 s[4:5], s[90:91]
	s_cbranch_execz .Lsp_post_end
	s_lshl_b32 s6, s92, 8
	s_add_u32 s6, s74, s6
	s_addc_u32 s7, s75, 0
	v_mov_b32_e32 v246, 0xd000
	v_mov_b32_e32 v247, 1
	global_atomic_add v248, v246, v247, s[6:7] sc0
	s_waitcnt vmcnt(0)
	v_lshrrev_b32_e32 v255, 5, v248
	v_and_b32_e32 v248, 31, v248
	v_cmp_eq_u32_e32 vcc, 31, v248
	s_and_saveexec_b64 s[8:9], vcc
	s_cbranch_execz .Lsp_post_nl
	v_mov_b32_e32 v246, 0xd800
	global_atomic_add v246, v247, s[6:7]

; __device__ __forceinline__ void attn_item(const Args& a, LAS unsigned char* lds, int item, int tid, int wave, int lane) {
;     ...
;     u32x4 kk[2][2], vv[2][2], qq[2][2]; f32x4 tk[2][4], tq[2][4];
; #pragma unroll
;     for (int it = 0; it < 2; ++it) {
;         const int t = tid + 512 * it;
;         const int kc = (t >> 2) < 192 ? (t >> 2) : 191, kpos = q0 - 128 + kc, kposc = kpos < 0 ? 0 : kpos;
;         const bf16_t* kp = P + (rowbase + kposc) * NIN + PC_KA + kvh * 64 + grp * 16; kk[it][0] = *(const u32x4*)kp; kk[it][1] = *(const u32x4*)(kp + 8);
;         const bf16_t* vp = P + (rowbase + kposc) * NIN + PC_VA + kvh * 64 + grp * 16; vv[it][0] = *(const u32x4*)vp; vv[it][1] = *(const u32x4*)(vp + 8);
;         const float* tkp = rope + (rowbase + kposc) * 16;
; #pragma unroll
;         for (int q = 0; q < 4; ++q) tk[it][q] = *(const f32x4*)(tkp + 4 * q);
;         const int qi = (t >> 2) & 63, gq = t >> 8;
;         const size_t row = rowbase + q0 + qi;
; __global__ void __launch_bounds__(NWAVES * 64, 2) fwd_megakernel(Args args) {
;     ...
;             for (int k = 0; k < 4; ++k) { const int l = myrank + 32 * k; attn_item(args, lds, ((2 * myx + (l >> 6)) << 6) | (l & 63), tid, wave, lane); }
.Lsp_post_end:
	s_or_b64 exec, exec, s[4:5]
	s_movk_i32 s1, 0x300
	v_cmp_gt_u32_e64 s[4:5], s1, v153
	v_add_u32_e32 v6, 0x200, v153
	s_movk_i32 s1, 0x100
	v_and_b32_e32 v1, 3, v153
	v_lshrrev_b32_e32 v3, 2, v153
	v_mov_b32_e32 v5, 0xbf
	v_lshrrev_b32_e32 v6, 2, v6
	v_cmp_gt_u32_e64 s[6:7], s1, v153
	v_cndmask_b32_e64 v93, v5, v3, s[4:5]
	s_movk_i32 s12, 0x18e0
	v_cndmask_b32_e64 v95, v5, v6, s[6:7]
	v_lshl_add_u32 v5, v1, 5, 0
	v_lshlrev_b32_e32 v4, 4, v1
	v_cmp_eq_u32_e64 s[8:9], 0, v1
	v_cmp_ne_u32_e64 s[10:11], 0, v1
	v_mad_u32_u24 v1, v1, s12, v5
	v_and_b32_e32 v94, 0xc0, v3
	v_and_b32_e32 v96, 0x1c0, v6
	v_sub_u32_e32 v97, 0x7f, v3
	v_mul_u32_u24_e32 v7, 0x90, v3
	v_lshl_add_u32 v98, v3, 1, v1
	v_mul_u32_u24_e32 v3, 0x90, v6
	v_lshl_add_u32 v99, v6, 1, v1
	v_lshlrev_b32_e32 v6, 2, v12
	s_lshl_b32 s0, s92, 7
	v_lshl_add_u32 v84, v0, 1, 0
	v_add_u32_e32 v101, 0, v0
	v_or_b32_e32 v0, 2, v6
	s_add_u32 s20, s74, 0x3100000
	v_readlane_b32 s12, v245, 10
	v_cmp_gt_u32_e64 s[16:17], v0, v92
	v_or_b32_e32 v0, 3, v6
	s_addc_u32 s21, s75, 0
	v_mov_b32_e32 v2, 0
	s_lshr_b32 s33, s12, 7
	s_lshl_b32 s12, s78, 5
	v_cmp_gt_u32_e64 s[18:19], v0, v92
	v_mbcnt_lo_u32_b32 v0, -1, 0
	v_bfe_u32 v85, v153, 2, 6
	s_mov_b32 s23, 0
	s_movk_i32 s1, 0x90
	s_and_b32 s38, s12, 32
	v_lshl_or_b32 v100, s33, 6, v92
	v_cmp_gt_u32_e64 s[12:13], v6, v92
	v_cmp_lt_u32_e64 s[14:15], v6, v92
	v_mul_u32_u24_e32 v102, 0x190, v92
	v_mul_i32_i24_e32 v103, 0x190, v56
	s_movk_i32 s39, 0x2400
	v_mov_b64_e32 v[86:87], s[68:69]
	v_lshlrev_b32_e32 v88, 1, v4
	v_mov_b32_e32 v89, v2
	s_mov_b64 s[24:25], 0x1000
	s_movk_i32 s40, 0x1000
	s_mov_b64 s[26:27], 0x1100
	v_mov_b32_e32 v104, 0x2400
	s_mov_b32 s41, 0xff800000
	v_lshlrev_b32_e32 v90, 1, v6
	s_mov_b64 s[28:29], 0x19800400
	s_mov_b32 s42, 0x19800000
	v_add_u32_e32 v105, v5, v7
	v_add_u32_e32 v106, v5, v3
	v_mbcnt_hi_u32_b32 v107, -1, v0
	v_mov_b32_e32 v108, 0xff800000
	s_mov_b32 s43, 0
	s_branch .LBB0_1088

; __device__ __forceinline__ unsigned xb_ld(unsigned* p)              { return __hip_atomic_load(p, __ATOMIC_RELAXED, __HIP_MEMORY_SCOPE_AGENT); }
; __device__ __forceinline__ unsigned xb_add(unsigned* p, unsigned v) { return __hip_atomic_fetch_add(p, v, __ATOMIC_RELAXED, __HIP_MEMORY_SCOPE_AGENT); }
; __device__ __forceinline__ void xcd_local_barrier(unsigned* xl, unsigned x) {
;     asm volatile("s_waitcnt vmcnt(0)" ::: "memory");
;     __syncthreads();
;     if (threadIdx.x == 0) {
;         __builtin_amdgcn_s_waitcnt(0);
;         unsigned* sub = xl + 512 + 64 * x; unsigned* gen = xl + 1024 + 64 * x;
;         const unsigned old = xb_add(sub, 1u), g = old / 32u;
;         if (old + 1u == (g + 1u) * 32u) (void)xb_add(gen, 1u);
;         else { unsigned sp = 0; while (xb_ld(gen) == g) { __builtin_amdgcn_s_sleep(1); if (++sp > (1u << 22)) break; } }
;         __builtin_amdgcn_fence(__ATOMIC_ACQUIRE, "agent");
;         asm volatile("s_waitcnt vmcnt(0)" ::: "memory");
;     }
;     __syncthreads();
; }
.LBB0_1163:
	s_and_b64 vcc, exec, s[4:5]
	s_cbranch_vccz .LBB0_1187
	s_and_saveexec_b64 s[4:5], s[90:91]
	s_cbranch_execz .Lsp_wait_end
	s_lshl_b32 s6, s92, 8
	s_add_u32 s6, s74, s6
	s_addc_u32 s7, s75, 0
	v_mov_b32_e32 v246, 0xd800
	s_mov_b32 s0, 0x40000
.Lsp_spin:
	global_load_dword v247, v246, s[6:7] sc1
	s_waitcnt vmcnt(0)
	v_cmp_ne_u32_e32 vcc, v247, v255
	s_cbranch_vccnz .Lsp_spun
	s_sleep 1
	s_sub_u32 s0, s0, 1
	s_cmp_lg_u32 s0, 0
	s_cbranch_scc1 .Lsp_spin
.Lsp_spun:
	buffer_inv sc1
	s_waitcnt vmcnt(0)

.LBB0_1456:
	s_ashr_i32 s21, s20, 31
	s_lshl_b64 s[22:23], s[20:21], 20
	s_add_u32 s22, s72, s22
	s_addc_u32 s23, s73, s23
	s_and_b64 s[24:25], s[4:5], exec
	s_cselect_b32 s21, s23, s31
	s_cselect_b32 s27, s22, s30
	s_ashr_i32 s19, s18, 31
	s_lshl_b64 s[24:25], s[18:19], 19
	s_add_u32 s24, s0, s24
	s_addc_u32 s25, s1, s25
	s_and_b64 s[36:37], s[4:5], exec
	s_cselect_b32 s19, s25, s35
	s_cselect_b32 s49, s24, s34
	s_add_u32 s30, s30, 0x80080
	s_addc_u32 s31, s31, 0
	s_add_u32 s50, s34, 0x100
	v_mov_b32_e32 v0, 0
	s_addc_u32 s51, s35, 0
	s_mov_b32 s52, -2
	s_waitcnt lgkmcnt(0)
	ds_read_b128 v[128:131], v191
	ds_read_b128 v[132:135], v191 offset:1024
	ds_read_b128 v[136:139], v191 offset:2048
	ds_read_b128 v[140:143], v191 offset:3072
	ds_read_b128 v[144:147], v192
	ds_read_b128 v[148:151], v192 offset:1024
	ds_read_b128 v[170:173], v192 offset:2048
	ds_read_b128 v[174:177], v192 offset:3072
	s_add_u32 s34, s30, 0xfff80080
	s_addc_u32 s35, s31, -1
	s_cmp_eq_u32 s52, 12
	s_cselect_b32 s37, s21, s35
	s_cselect_b32 s36, s27, s34
	s_cselect_b32 s35, s19, s51
	s_cselect_b32 s34, s49, s50
	v_lshl_add_u64 v[186:187], s[30:31], 0, v[162:163]
	s_add_i32 m0, s29, 0xc000
	ds_read_b128 v[178:181], v193
	ds_read_b128 v[182:185], v193 offset:1024
	ds_read_b128 v[196:199], v193 offset:2048
	ds_read_b128 v[200:203], v193 offset:3072
	ds_read_b128 v[204:207], v193 offset:4096
	ds_read_b128 v[208:211], v193 offset:5120
	ds_read_b128 v[212:215], v193 offset:6144
	ds_read_b128 v[216:219], v193 offset:7168
	global_load_lds_dwordx4 v[186:187], off
	v_lshl_add_u64 v[186:187], s[30:31], 0, v[164:165]
	s_add_i32 m0, s29, 0xe000
	s_nop 0
	global_load_lds_dwordx4 v[186:187], off
	s_cmp_eq_u32 s101, 1
	s_cbranch_scc1 .Lpk1457_r1
	s_waitcnt vmcnt(8)
	s_branch .Lpk1457_j1

.Lpk1457_j1:
	s_waitcnt lgkmcnt(0)
	s_barrier
	s_setprio 1
	s_waitcnt lgkmcnt(0)
	v_mfma_f32_16x16x32_bf16 v[124:127], v[128:131], v[178:181], 0
	v_mfma_f32_16x16x32_bf16 v[120:123], v[136:139], v[178:181], 0
	v_mfma_f32_16x16x32_bf16 v[108:111], v[128:131], v[196:199], 0
	v_mfma_f32_16x16x32_bf16 v[104:107], v[136:139], v[196:199], 0
	v_mfma_f32_16x16x32_bf16 v[92:95], v[128:131], v[204:207], 0
	v_mfma_f32_16x16x32_bf16 v[88:91], v[136:139], v[204:207], 0
	v_mfma_f32_16x16x32_bf16 v[76:79], v[128:131], v[212:215], 0
	v_mfma_f32_16x16x32_bf16 v[72:75], v[136:139], v[212:215], 0
	v_mfma_f32_16x16x32_bf16 v[124:127], v[132:135], v[182:185], v[124:127]
	v_mfma_f32_16x16x32_bf16 v[120:123], v[140:143], v[182:185], v[120:123]
	v_mfma_f32_16x16x32_bf16 v[108:111], v[132:135], v[200:203], v[108:111]
	v_mfma_f32_16x16x32_bf16 v[104:107], v[140:143], v[200:203], v[104:107]
	v_mfma_f32_16x16x32_bf16 v[92:95], v[132:135], v[208:211], v[92:95]
	v_mfma_f32_16x16x32_bf16 v[88:91], v[140:143], v[208:211], v[88:91]
	v_mfma_f32_16x16x32_bf16 v[76:79], v[132:135], v[216:219], v[76:79]
	v_mfma_f32_16x16x32_bf16 v[72:75], v[140:143], v[216:219], v[72:75]
	s_setprio 0
	s_setprio 1
	v_mfma_f32_16x16x32_bf16 v[116:119], v[144:147], v[178:181], 0
	v_mfma_f32_16x16x32_bf16 v[112:115], v[170:173], v[178:181], 0
	v_mfma_f32_16x16x32_bf16 v[100:103], v[144:147], v[196:199], 0
	v_mfma_f32_16x16x32_bf16 v[96:99], v[170:173], v[196:199], 0
	v_mfma_f32_16x16x32_bf16 v[84:87], v[144:147], v[204:207], 0
	v_mfma_f32_16x16x32_bf16 v[80:83], v[170:173], v[204:207], 0
	v_mfma_f32_16x16x32_bf16 v[68:71], v[144:147], v[212:215], 0
	v_mfma_f32_16x16x32_bf16 v[64:67], v[170:173], v[212:215], 0
	v_mfma_f32_16x16x32_bf16 v[116:119], v[148:151], v[182:185], v[116:119]
	v_mfma_f32_16x16x32_bf16 v[112:115], v[174:177], v[182:185], v[112:115]
	v_mfma_f32_16x16x32_bf16 v[100:103], v[148:151], v[200:203], v[100:103]
	v_mfma_f32_16x16x32_bf16 v[96:99], v[174:177], v[200:203], v[96:99]
	v_mfma_f32_16x16x32_bf16 v[84:87], v[148:151], v[208:211], v[84:87]
	v_mfma_f32_16x16x32_bf16 v[80:83], v[174:177], v[208:211], v[80:83]
	v_mfma_f32_16x16x32_bf16 v[68:71], v[148:151], v[216:219], v[68:71]
	v_mfma_f32_16x16x32_bf16 v[64:67], v[174:177], v[216:219], v[64:67]
	s_setprio 0
	s_barrier
	s_add_i32 s53, s47, s33
	v_lshl_add_u64 v[186:187], s[34:35], 0, v[156:157]
	s_mov_b32 m0, s53
	ds_read_b128 v[178:181], v193 offset:16384
	ds_read_b128 v[182:185], v193 offset:17408
	global_load_lds_dwordx4 v[186:187], off
	s_add_i32 m0, s53, 0x2000
	s_add_u32 s54, s34, 0x40000
	v_lshl_add_u64 v[220:221], s[34:35], 0, v[160:161]
	s_addc_u32 s55, s35, 0
	s_add_i32 s53, s48, s33
	ds_read_b128 v[196:199], v193 offset:18432
	ds_read_b128 v[200:203], v193 offset:19456
	global_load_lds_dwordx4 v[220:221], off
	v_lshl_add_u64 v[222:223], s[54:55], 0, v[156:157]
	s_mov_b32 m0, s53
	v_lshl_add_u64 v[224:225], s[36:37], 0, v[158:159]
	ds_read_b128 v[204:207], v193 offset:20480
	global_load_lds_dwordx4 v[222:223], off
	v_lshl_add_u64 v[222:223], s[54:55], 0, v[160:161]
	s_add_i32 m0, s53, 0x2000
	ds_read_b128 v[208:211], v193 offset:21504
	global_load_lds_dwordx4 v[222:223], off
	v_lshl_add_u64 v[222:223], s[36:37], 0, v[154:155]
	s_mov_b32 m0, s29
	ds_read_b128 v[212:215], v193 offset:22528
	global_load_lds_dwordx4 v[222:223], off
	s_mov_b32 m0, s38
	ds_read_b128 v[216:219], v193 offset:23552
	global_load_lds_dwordx4 v[224:225], off
	s_cmp_eq_u32 s101, 1
	s_cbranch_scc1 .Lpk1457_r2
	s_waitcnt vmcnt(8)
	s_branch .Lpk1457_j2

; __device__ __forceinline__ unsigned cvt_pk_bf16(float lo, float hi) { unsigned r; asm volatile("v_cvt_pk_bf16_f32 %0, %1, %2" : "=v"(r) : "v"(lo), "v"(hi)); return r; }
; __device__ __forceinline__ float bflo(unsigned w) { return __uint_as_float(w << 16); }
; __device__ __forceinline__ float bfhi(unsigned w) { return __uint_as_float(w & 0xffff0000u); }
;     __device__ __forceinline__ void operator()(Acc& acc, const Unit& u, int wr, int wc, int fr, int fq) const { scale(acc, u, wr, wc, fr, fq, PC_GA, true); }
;     __device__ __forceinline__ void operator()(Acc& acc, const Unit& u, int wr, int wc, int fr, int fq) const {
;         const int row0 = u.pm * BM + wr * 64 + fr, col0 = u.pn * BM + wc * 32 + 8 * fq;
; #pragma unroll
;         for (int ai = 0; ai < 2; ++ai) {
;             f32x4 b[4][2][2];
; #pragma unroll
;             for (int m = 0; m < 4; ++m)
; #pragma unroll
;                 for (int bj = 0; bj < 2; ++bj) {
;                     const size_t p = (size_t)(row0 + ai * HALF + m * 16) * DM + col0 + bj * HALF;
;                     if constexpr (BASE_BF16) { const u32x4 w = *(const u32x4*)((const bf16_t*)base + p); b[m][bj][0] = (f32x4){bflo(w.x), bfhi(w.x), bflo(w.y), bfhi(w.y)}; b[m][bj][1] = (f32x4){bflo(w.z), bfhi(w.z), bflo(w.w), bfhi(w.w)}; }
;                     else { b[m][bj][0] = *(const f32x4*)((const float*)base + p); b[m][bj][1] = *(const f32x4*)((const float*)base + p + 4); }
;                 }
; #pragma unroll
;             for (int m = 0; m < 4; ++m) {
;                 const int row = row0 + ai * HALF + m * 16; float sq = 0.f;
; #pragma unroll
;                 for (int bj = 0; bj < 2; ++bj) {
;                     const size_t p = (size_t)row * DM + col0 + bj * HALF;
;                     const f32x4 v0 = b[m][bj][0] + acc[ai][bj][m][0] * scale, v1 = b[m][bj][1] + acc[ai][bj][m][1] * scale;
;                     u32x4 w; w.x = cvt_pk_bf16(v0[0], v0[1]); w.y = cvt_pk_bf16(v0[2], v0[3]); w.z = cvt_pk_bf16(v1[0], v1[1]); w.w = cvt_pk_bf16(v1[2], v1[3]); *(u32x4*)(xb + p) = w;
;                     sq += (v0[0] * v0[0] + v0[1] * v0[1]) + (v0[2] * v0[2] + v0[3] * v0[3]) + (v1[0] * v1[0] + v1[1] * v1[1]) + (v1[2] * v1[2] + v1[3] * v1[3]);
;                 }
;                 sq += __shfl_xor(sq, 16); sq += __shfl_xor(sq, 32);
;                 if (fq == 0) atomicAdd(ss + row, sq);
;             }
.LBB0_1460:
	v_lshl_or_b32 v170, s28, 8, v190
	v_lshl_add_u32 v174, s26, 8, v188
	v_ashrrev_i32_e32 v171, 31, v170
	v_lshlrev_b64 v[204:205], 1, v[170:171]
	v_ashrrev_i32_e32 v175, 31, v174
	v_lshl_add_u64 v[172:173], s[10:11], 0, v[204:205]
	v_lshlrev_b64 v[206:207], 11, v[174:175]
	v_lshl_add_u64 v[128:129], v[172:173], 0, v[206:207]
	global_load_dwordx4 v[196:199], v[128:129], off
	global_load_dwordx4 v[200:203], v[128:129], off offset:256
	v_or_b32_e32 v184, 16, v174
	v_or_b32_e32 v180, 32, v174
	v_or_b32_e32 v176, 48, v174
	v_ashrrev_i32_e32 v185, 31, v184
	v_ashrrev_i32_e32 v181, 31, v180
	v_ashrrev_i32_e32 v177, 31, v176
	v_lshlrev_b64 v[186:187], 11, v[184:185]
	v_lshlrev_b64 v[182:183], 11, v[180:181]
	v_lshlrev_b64 v[178:179], 11, v[176:177]
	v_lshl_add_u64 v[128:129], v[172:173], 0, v[186:187]
	v_lshl_add_u64 v[130:131], v[172:173], 0, v[182:183]
	v_lshl_add_u64 v[208:209], v[172:173], 0, v[178:179]
	global_load_dwordx4 v[148:151], v[128:129], off
	global_load_dwordx4 v[144:147], v[128:129], off offset:256
	global_load_dwordx4 v[140:143], v[130:131], off
	global_load_dwordx4 v[136:139], v[130:131], off offset:256
	global_load_dwordx4 v[132:135], v[208:209], off
	s_nop 0
	global_load_dwordx4 v[128:131], v[208:209], off offset:256
	v_add_u32_e32 v250, 0x80, v174
	v_ashrrev_i32_e32 v251, 31, v250
	v_lshlrev_b64 v[252:253], 11, v[250:251]
	v_lshl_add_u64 v[254:255], v[172:173], 0, v[252:253]
	global_load_dwordx4 v[216:219], v[254:255], off
	global_load_dwordx4 v[220:223], v[254:255], off offset:256
	v_add_u32_e32 v250, 0x90, v174
	v_ashrrev_i32_e32 v251, 31, v250
	v_lshlrev_b64 v[252:253], 11, v[250:251]
	v_lshl_add_u64 v[254:255], v[172:173], 0, v[252:253]
	global_load_dwordx4 v[224:227], v[254:255], off
	global_load_dwordx4 v[228:231], v[254:255], off offset:256
	v_add_u32_e32 v250, 0xa0, v174
	v_ashrrev_i32_e32 v251, 31, v250
	v_lshlrev_b64 v[252:253], 11, v[250:251]
	v_lshl_add_u64 v[254:255], v[172:173], 0, v[252:253]
	global_load_dwordx4 v[232:235], v[254:255], off
	global_load_dwordx4 v[236:239], v[254:255], off offset:256
	v_add_u32_e32 v250, 0xb0, v174
	v_ashrrev_i32_e32 v251, 31, v250
	v_lshlrev_b64 v[252:253], 11, v[250:251]
	v_lshl_add_u64 v[254:255], v[172:173], 0, v[252:253]
	global_load_dwordx4 v[240:243], v[254:255], off
	global_load_dwordx4 v[246:249], v[254:255], off offset:256
	v_and_b32_e32 v208, 64, v194
	v_xor_b32_e32 v195, 16, v194
	v_add_u32_e32 v208, 64, v208
	v_xor_b32_e32 v209, 32, v194
	v_cmp_lt_i32_e32 vcc, v195, v208
	v_lshl_add_u64 v[206:207], s[12:13], 0, v[206:207]
	v_lshl_add_u64 v[204:205], v[206:207], 0, v[204:205]
	v_cndmask_b32_e32 v195, v194, v195, vcc
	v_cmp_lt_i32_e32 vcc, v209, v208
	v_lshlrev_b32_e32 v195, 2, v195
	s_waitcnt vmcnt(0)
	v_lshlrev_b32_e32 v206, 16, v196
	v_and_b32_e32 v207, 0xffff0000, v196
	v_lshlrev_b32_e32 v196, 16, v197
	v_and_b32_e32 v197, 0xffff0000, v197
	v_lshlrev_b32_e32 v210, 16, v200
	v_and_b32_e32 v211, 0xffff0000, v200
	v_lshlrev_b32_e32 v200, 16, v201
	v_and_b32_e32 v201, 0xffff0000, v201
	v_cndmask_b32_e32 v214, v194, v209, vcc
	v_lshlrev_b32_e32 v208, 16, v198
	v_and_b32_e32 v209, 0xffff0000, v198
	v_lshlrev_b32_e32 v198, 16, v199
	v_and_b32_e32 v199, 0xffff0000, v199
	v_lshlrev_b32_e32 v212, 16, v202
	v_and_b32_e32 v213, 0xffff0000, v202
	v_lshlrev_b32_e32 v202, 16, v203
	v_and_b32_e32 v203, 0xffff0000, v203
	v_pk_add_f32 v[126:127], v[126:127], v[196:197]
	v_pk_add_f32 v[124:125], v[124:125], v[206:207]
	v_pk_add_f32 v[118:119], v[118:119], v[200:201]
	v_pk_add_f32 v[116:117], v[116:117], v[210:211]
	v_pk_add_f32 v[122:123], v[122:123], v[198:199]
	v_pk_add_f32 v[120:121], v[120:121], v[208:209]
	v_pk_add_f32 v[196:197], v[114:115], v[202:203]
	v_pk_add_f32 v[198:199], v[112:113], v[212:213]
	v_mul_f32_e32 v114, v125, v125
	v_mul_f32_e32 v115, v127, v127
	v_mul_f32_e32 v200, v117, v117
	v_mul_f32_e32 v201, v119, v119
	v_cvt_pk_bf16_f32 v112, v124, v125
	v_mul_f32_e32 v125, v121, v121
	v_mul_f32_e32 v202, v199, v199
	v_fmac_f32_e32 v114, v124, v124
	v_fmac_f32_e32 v115, v126, v126
	v_fmac_f32_e32 v200, v116, v116
	v_fmac_f32_e32 v201, v118, v118
	v_cvt_pk_bf16_f32 v113, v126, v127
	v_mul_f32_e32 v127, v123, v123
	v_mul_f32_e32 v203, v197, v197
	v_fmac_f32_e32 v125, v120, v120
	v_fmac_f32_e32 v202, v198, v198
	v_add_f32_e32 v114, v114, v115
	v_add_f32_e32 v115, v200, v201
	v_fmac_f32_e32 v127, v122, v122
	v_fmac_f32_e32 v203, v196, v196
	v_add_f32_e32 v114, v125, v114
	v_add_f32_e32 v115, v202, v115
	v_add_f32_e32 v114, v127, v114
	v_add_f32_e32 v115, v203, v115
	v_add_f32_e32 v124, v114, v115
	ds_bpermute_b32 v125, v195, v124
	v_cvt_pk_bf16_f32 v114, v120, v121
	v_cvt_pk_bf16_f32 v115, v122, v123
	global_store_dwordx4 v[204:205], v[112:115], off
	v_cvt_pk_bf16_f32 v116, v116, v117
	v_cvt_pk_bf16_f32 v117, v118, v119
	v_cvt_pk_bf16_f32 v118, v198, v199
	v_cvt_pk_bf16_f32 v119, v196, v197
	global_store_dwordx4 v[204:205], v[116:119], off offset:256
	s_waitcnt lgkmcnt(0)
	v_add_f32_e32 v113, v124, v125
	v_lshlrev_b32_e32 v112, 2, v214
	ds_bpermute_b32 v114, v112, v113
	s_and_saveexec_b64 s[26:27], s[2:3]
	s_cbranch_execz .LBB0_1462
	v_lshl_add_u64 v[116:117], v[174:175], 2, s[6:7]
	s_waitcnt lgkmcnt(0)
	v_add_f32_e32 v113, v113, v114
	global_atomic_add_f32 v[116:117], v113, off

; __device__ __forceinline__ unsigned cvt_pk_bf16(float lo, float hi) { unsigned r; asm volatile("v_cvt_pk_bf16_f32 %0, %1, %2" : "=v"(r) : "v"(lo), "v"(hi)); return r; }
;     __device__ __forceinline__ void operator()(Acc& acc, const Unit& u, int wr, int wc, int fr, int fq) const {
;     ...
;             for (int m = 0; m < 4; ++m) {
;                 const int row = row0 + ai * HALF + m * 16; float sq = 0.f;
; #pragma unroll
;                 for (int bj = 0; bj < 2; ++bj) {
;                     const size_t p = (size_t)row * DM + col0 + bj * HALF;
;                     const f32x4 v0 = b[m][bj][0] + acc[ai][bj][m][0] * scale, v1 = b[m][bj][1] + acc[ai][bj][m][1] * scale;
;                     u32x4 w; w.x = cvt_pk_bf16(v0[0], v0[1]); w.y = cvt_pk_bf16(v0[2], v0[3]); w.z = cvt_pk_bf16(v1[0], v1[1]); w.w = cvt_pk_bf16(v1[2], v1[3]); *(u32x4*)(xb + p) = w;
;                     sq += (v0[0] * v0[0] + v0[1] * v0[1]) + (v0[2] * v0[2] + v0[3] * v0[3]) + (v1[0] * v1[0] + v1[1] * v1[1]) + (v1[2] * v1[2] + v1[3] * v1[3]);
;                 }
;                 sq += __shfl_xor(sq, 16); sq += __shfl_xor(sq, 32);
;                 if (fq == 0) atomicAdd(ss + row, sq);
;             }
.LBB0_1468:
	s_or_b64 exec, exec, s[26:27]
	v_add_u32_e32 v100, 0x80, v174
	v_ashrrev_i32_e32 v101, 31, v100
	v_lshlrev_b64 v[110:111], 11, v[100:101]
	s_waitcnt lgkmcnt(0)
	v_lshl_add_u64 v[64:65], v[172:173], 0, v[110:111]
	v_add_u32_e32 v96, 0x90, v174
	v_add_u32_e32 v92, 0xa0, v174
	v_add_u32_e32 v88, 0xb0, v174
	v_ashrrev_i32_e32 v97, 31, v96
	v_ashrrev_i32_e32 v93, 31, v92
	v_ashrrev_i32_e32 v89, 31, v88
	v_lshlrev_b64 v[98:99], 11, v[96:97]
	v_lshlrev_b64 v[94:95], 11, v[92:93]
	v_lshlrev_b64 v[90:91], 11, v[88:89]
	v_lshl_add_u64 v[64:65], v[172:173], 0, v[98:99]
	v_lshl_add_u64 v[66:67], v[172:173], 0, v[94:95]
	v_lshl_add_u64 v[114:115], v[172:173], 0, v[90:91]
	v_mov_b32_e32 v102, v216
	v_mov_b32_e32 v103, v217
	v_mov_b32_e32 v104, v218
	v_mov_b32_e32 v105, v219
	v_mov_b32_e32 v106, v220
	v_mov_b32_e32 v107, v221
	v_mov_b32_e32 v108, v222
	v_mov_b32_e32 v109, v223
	v_mov_b32_e32 v84, v224
	v_mov_b32_e32 v85, v225
	v_mov_b32_e32 v86, v226
	v_mov_b32_e32 v87, v227
	v_mov_b32_e32 v80, v228
	v_mov_b32_e32 v81, v229
	v_mov_b32_e32 v82, v230
	v_mov_b32_e32 v83, v231
	v_mov_b32_e32 v76, v232
	v_mov_b32_e32 v77, v233
	v_mov_b32_e32 v78, v234
	v_mov_b32_e32 v79, v235
	v_mov_b32_e32 v72, v236
	v_mov_b32_e32 v73, v237
	v_mov_b32_e32 v74, v238
	v_mov_b32_e32 v75, v239
	v_mov_b32_e32 v68, v240
	v_mov_b32_e32 v69, v241
	v_mov_b32_e32 v70, v242
	v_mov_b32_e32 v71, v243
	v_mov_b32_e32 v64, v246
	v_mov_b32_e32 v65, v247
	v_mov_b32_e32 v66, v248
	v_mov_b32_e32 v67, v249
	v_lshlrev_b32_e32 v114, 16, v102
	v_and_b32_e32 v115, 0xffff0000, v102
	v_lshlrev_b32_e32 v102, 16, v103
	v_and_b32_e32 v103, 0xffff0000, v103
	v_lshlrev_b32_e32 v118, 16, v106
	v_and_b32_e32 v119, 0xffff0000, v106
	v_lshlrev_b32_e32 v106, 16, v107
	v_and_b32_e32 v107, 0xffff0000, v107
	v_lshlrev_b32_e32 v116, 16, v104
	v_and_b32_e32 v117, 0xffff0000, v104
	v_lshlrev_b32_e32 v104, 16, v105
	v_and_b32_e32 v105, 0xffff0000, v105
	v_lshlrev_b32_e32 v120, 16, v108
	v_and_b32_e32 v121, 0xffff0000, v108
	v_pk_add_f32 v[62:63], v[62:63], v[102:103]
	v_pk_add_f32 v[60:61], v[60:61], v[114:115]
	v_pk_add_f32 v[54:55], v[54:55], v[106:107]
	v_pk_add_f32 v[52:53], v[52:53], v[118:119]
	v_lshlrev_b32_e32 v108, 16, v109
	v_and_b32_e32 v109, 0xffff0000, v109
	v_pk_add_f32 v[58:59], v[58:59], v[104:105]
	v_pk_add_f32 v[56:57], v[56:57], v[116:117]
	v_pk_add_f32 v[104:105], v[48:49], v[120:121]
	v_cvt_pk_bf16_f32 v48, v60, v61
	v_cvt_pk_bf16_f32 v49, v62, v63
	v_mul_f32_e32 v61, v61, v61
	v_mul_f32_e32 v63, v63, v63
	v_mul_f32_e32 v106, v53, v53
	v_mul_f32_e32 v107, v55, v55
	v_pk_add_f32 v[102:103], v[50:51], v[108:109]
	v_cvt_pk_bf16_f32 v50, v56, v57
	v_cvt_pk_bf16_f32 v51, v58, v59
	v_mul_f32_e32 v57, v57, v57
	v_mul_f32_e32 v59, v59, v59
	v_mul_f32_e32 v108, v105, v105
	v_fmac_f32_e32 v61, v60, v60
	v_fmac_f32_e32 v63, v62, v62
	v_fmac_f32_e32 v106, v52, v52
	v_fmac_f32_e32 v107, v54, v54
	v_mul_f32_e32 v109, v103, v103
	v_fmac_f32_e32 v57, v56, v56
	v_fmac_f32_e32 v59, v58, v58
	v_fmac_f32_e32 v108, v104, v104
	v_add_f32_e32 v56, v61, v63
	v_add_f32_e32 v58, v106, v107
	v_fmac_f32_e32 v109, v102, v102
	v_add_f32_e32 v56, v57, v56
	v_add_f32_e32 v57, v108, v58
	v_add_f32_e32 v56, v59, v56
	v_add_f32_e32 v57, v109, v57
	v_add_f32_e32 v58, v56, v57
	ds_bpermute_b32 v59, v195, v58
	v_lshl_add_u64 v[56:57], s[12:13], 0, v[110:111]
	v_lshl_add_u64 v[56:57], v[170:171], 1, v[56:57]
	global_store_dwordx4 v[56:57], v[48:51], off
	s_waitcnt lgkmcnt(0)
	s_nop 0
	v_add_f32_e32 v48, v58, v59
	ds_bpermute_b32 v49, v112, v48
	v_cvt_pk_bf16_f32 v50, v52, v53
	v_cvt_pk_bf16_f32 v51, v54, v55
	v_cvt_pk_bf16_f32 v52, v104, v105
	v_cvt_pk_bf16_f32 v53, v102, v103
	global_store_dwordx4 v[56:57], v[50:53], off offset:256
	s_and_saveexec_b64 s[26:27], s[2:3]
	s_cbranch_execz .LBB0_1470
	v_lshl_add_u64 v[50:51], v[100:101], 2, s[6:7]
	s_waitcnt lgkmcnt(0)
	v_add_f32_e32 v48, v48, v49
	global_atomic_add_f32 v[50:51], v48, off
.LBB0_1470:
	s_or_b64 exec, exec, s[26:27]
	v_lshlrev_b32_e32 v48, 16, v84
	s_waitcnt lgkmcnt(0)
	v_and_b32_e32 v49, 0xffff0000, v84
	v_lshlrev_b32_e32 v50, 16, v85
	v_and_b32_e32 v51, 0xffff0000, v85
	v_lshlrev_b32_e32 v52, 16, v86
	v_and_b32_e32 v53, 0xffff0000, v86
	v_pk_add_f32 v[44:45], v[44:45], v[48:49]
	v_pk_add_f32 v[46:47], v[46:47], v[50:51]
	v_pk_add_f32 v[50:51], v[40:41], v[52:53]
	v_cvt_pk_bf16_f32 v40, v44, v45
	v_mul_f32_e32 v45, v45, v45
	v_fmac_f32_e32 v45, v44, v44
	v_mul_f32_e32 v44, v47, v47
	v_lshlrev_b32_e32 v56, 16, v80
	v_and_b32_e32 v57, 0xffff0000, v80
	v_lshlrev_b32_e32 v58, 16, v81
	v_and_b32_e32 v59, 0xffff0000, v81
	v_fmac_f32_e32 v44, v46, v46
	v_lshlrev_b32_e32 v54, 16, v87
	v_and_b32_e32 v55, 0xffff0000, v87
	v_lshlrev_b32_e32 v60, 16, v82
	v_and_b32_e32 v61, 0xffff0000, v82
	v_add_f32_e32 v44, v45, v44
	v_mul_f32_e32 v45, v51, v51
	v_pk_add_f32 v[38:39], v[38:39], v[58:59]
	v_pk_add_f32 v[36:37], v[36:37], v[56:57]
	v_pk_add_f32 v[48:49], v[42:43], v[54:55]
	v_cvt_pk_bf16_f32 v41, v46, v47
	v_fmac_f32_e32 v45, v50, v50
	v_pk_add_f32 v[46:47], v[32:33], v[60:61]
	v_mul_f32_e32 v32, v37, v37
	v_mul_f32_e32 v33, v39, v39
	v_add_f32_e32 v44, v45, v44
	v_mul_f32_e32 v45, v49, v49
	v_fmac_f32_e32 v32, v36, v36
	v_fmac_f32_e32 v33, v38, v38
	v_lshlrev_b32_e32 v62, 16, v83
	v_and_b32_e32 v63, 0xffff0000, v83
	v_fmac_f32_e32 v45, v48, v48
	v_add_f32_e32 v32, v32, v33
	v_mul_f32_e32 v33, v47, v47
	v_cvt_pk_bf16_f32 v42, v50, v51
	v_cvt_pk_bf16_f32 v43, v48, v49
	v_add_f32_e32 v48, v45, v44
	v_pk_add_f32 v[44:45], v[34:35], v[62:63]
	v_fmac_f32_e32 v33, v46, v46
	v_add_f32_e32 v32, v33, v32
	v_mul_f32_e32 v33, v45, v45
	v_fmac_f32_e32 v33, v44, v44
	v_add_f32_e32 v32, v33, v32
	v_add_f32_e32 v35, v48, v32
	ds_bpermute_b32 v50, v195, v35
	v_lshl_add_u64 v[32:33], s[12:13], 0, v[98:99]
	v_lshl_add_u64 v[48:49], v[170:171], 1, v[32:33]
	global_store_dwordx4 v[48:49], v[40:43], off
	v_cvt_pk_bf16_f32 v34, v36, v37
	s_waitcnt lgkmcnt(0)
	v_add_f32_e32 v32, v35, v50
	ds_bpermute_b32 v33, v112, v32
	v_cvt_pk_bf16_f32 v35, v38, v39
	v_cvt_pk_bf16_f32 v36, v46, v47
	v_cvt_pk_bf16_f32 v37, v44, v45
	global_store_dwordx4 v[48:49], v[34:37], off offset:256
	s_and_saveexec_b64 s[26:27], s[2:3]
	s_cbranch_execz .LBB0_1472
	v_lshl_add_u64 v[34:35], v[96:97], 2, s[6:7]
	s_waitcnt lgkmcnt(0)
	v_add_f32_e32 v32, v32, v33
	global_atomic_add_f32 v[34:35], v32, off
; __device__ __forceinline__ unsigned cvt_pk_bf16(float lo, float hi) { unsigned r; asm volatile("v_cvt_pk_bf16_f32 %0, %1, %2" : "=v"(r) : "v"(lo), "v"(hi)); return r; }
; #define PG8_WAIT_V(n) asm volatile("s_waitcnt vmcnt(" #n ")" ::: "memory")
; #define PG8_BAR __builtin_amdgcn_s_barrier()
;     __device__ __forceinline__ void operator()(Acc& acc, const Unit& u, int wr, int wc, int fr, int fq) const {
;     ...
;             for (int m = 0; m < 4; ++m) {
;                 const int row = row0 + ai * HALF + m * 16; float sq = 0.f;
; #pragma unroll
;                 for (int bj = 0; bj < 2; ++bj) {
;                     const size_t p = (size_t)row * DM + col0 + bj * HALF;
;                     const f32x4 v0 = b[m][bj][0] + acc[ai][bj][m][0] * scale, v1 = b[m][bj][1] + acc[ai][bj][m][1] * scale;
;                     u32x4 w; w.x = cvt_pk_bf16(v0[0], v0[1]); w.y = cvt_pk_bf16(v0[2], v0[3]); w.z = cvt_pk_bf16(v1[0], v1[1]); w.w = cvt_pk_bf16(v1[2], v1[3]); *(u32x4*)(xb + p) = w;
;                     sq += (v0[0] * v0[0] + v0[1] * v0[1]) + (v0[2] * v0[2] + v0[3] * v0[3]) + (v1[0] * v1[0] + v1[1] * v1[1]) + (v1[2] * v1[2] + v1[3] * v1[3]);
;                 }
;                 sq += __shfl_xor(sq, 16); sq += __shfl_xor(sq, 32);
;                 if (fq == 0) atomicAdd(ss + row, sq);
;             }
; template <class Epi, class Sched, bool ALIGN_EPI>
; __device__ __forceinline__ void gemm_phase(LAS unsigned char* lds, const Gemm g, const Sched& S, const Epi& E) {
;     ...
;         cur = nxt; cA = nA; cB = nB; ++ui;
;         if constexpr (ALIGN_EPI) { if (wr == 1) PG8_BAR; }
;     }
;     PG8_WAIT_V(0);
;     if constexpr (!ALIGN_EPI) { if (wr == 0) PG8_BAR; }
;     PG8_BAR;
.LBB0_1472:
	s_or_b64 exec, exec, s[26:27]
	v_lshlrev_b32_e32 v32, 16, v76
	s_waitcnt lgkmcnt(0)
	v_and_b32_e32 v33, 0xffff0000, v76
	v_lshlrev_b32_e32 v34, 16, v77
	v_and_b32_e32 v35, 0xffff0000, v77
	v_lshlrev_b32_e32 v36, 16, v78
	v_and_b32_e32 v37, 0xffff0000, v78
	v_pk_add_f32 v[28:29], v[28:29], v[32:33]
	v_pk_add_f32 v[30:31], v[30:31], v[34:35]
	v_pk_add_f32 v[34:35], v[24:25], v[36:37]
	v_cvt_pk_bf16_f32 v24, v28, v29
	v_mul_f32_e32 v29, v29, v29
	v_fmac_f32_e32 v29, v28, v28
	v_mul_f32_e32 v28, v31, v31
	v_lshlrev_b32_e32 v40, 16, v72
	v_and_b32_e32 v41, 0xffff0000, v72
	v_lshlrev_b32_e32 v42, 16, v73
	v_and_b32_e32 v43, 0xffff0000, v73
	v_fmac_f32_e32 v28, v30, v30
	v_lshlrev_b32_e32 v38, 16, v79
	v_and_b32_e32 v39, 0xffff0000, v79
	v_lshlrev_b32_e32 v44, 16, v74
	v_and_b32_e32 v45, 0xffff0000, v74
	v_add_f32_e32 v28, v29, v28
	v_mul_f32_e32 v29, v35, v35
	v_pk_add_f32 v[22:23], v[22:23], v[42:43]
	v_pk_add_f32 v[20:21], v[20:21], v[40:41]
	v_pk_add_f32 v[32:33], v[26:27], v[38:39]
	v_cvt_pk_bf16_f32 v25, v30, v31
	v_fmac_f32_e32 v29, v34, v34
	v_pk_add_f32 v[30:31], v[16:17], v[44:45]
	v_mul_f32_e32 v16, v21, v21
	v_mul_f32_e32 v17, v23, v23
	v_add_f32_e32 v28, v29, v28
	v_mul_f32_e32 v29, v33, v33
	v_fmac_f32_e32 v16, v20, v20
	v_fmac_f32_e32 v17, v22, v22
	v_lshlrev_b32_e32 v46, 16, v75
	v_and_b32_e32 v47, 0xffff0000, v75
	v_fmac_f32_e32 v29, v32, v32
	v_add_f32_e32 v16, v16, v17
	v_mul_f32_e32 v17, v31, v31
	v_cvt_pk_bf16_f32 v26, v34, v35
	v_cvt_pk_bf16_f32 v27, v32, v33
	v_add_f32_e32 v32, v29, v28
	v_pk_add_f32 v[28:29], v[18:19], v[46:47]
	v_fmac_f32_e32 v17, v30, v30
	v_add_f32_e32 v16, v17, v16
	v_mul_f32_e32 v17, v29, v29
	v_fmac_f32_e32 v17, v28, v28
	v_add_f32_e32 v16, v17, v16
	v_add_f32_e32 v19, v32, v16
	ds_bpermute_b32 v34, v195, v19
	v_lshl_add_u64 v[16:17], s[12:13], 0, v[94:95]
	v_lshl_add_u64 v[32:33], v[170:171], 1, v[16:17]
	global_store_dwordx4 v[32:33], v[24:27], off
	v_cvt_pk_bf16_f32 v18, v20, v21
	s_waitcnt lgkmcnt(0)
	v_add_f32_e32 v16, v19, v34
	ds_bpermute_b32 v17, v112, v16
	v_cvt_pk_bf16_f32 v19, v22, v23
	v_cvt_pk_bf16_f32 v20, v30, v31
	v_cvt_pk_bf16_f32 v21, v28, v29
	global_store_dwordx4 v[32:33], v[18:21], off offset:256
	s_and_saveexec_b64 s[26:27], s[2:3]
	s_cbranch_execz .LBB0_1474
	v_lshl_add_u64 v[18:19], v[92:93], 2, s[6:7]
	s_waitcnt lgkmcnt(0)
	v_add_f32_e32 v16, v16, v17
	global_atomic_add_f32 v[18:19], v16, off
.LBB0_1474:
	s_or_b64 exec, exec, s[26:27]
	v_lshlrev_b32_e32 v16, 16, v68
	s_waitcnt lgkmcnt(0)
	v_and_b32_e32 v17, 0xffff0000, v68
	v_lshlrev_b32_e32 v18, 16, v69
	v_and_b32_e32 v19, 0xffff0000, v69
	v_lshlrev_b32_e32 v20, 16, v70
	v_and_b32_e32 v21, 0xffff0000, v70
	v_pk_add_f32 v[12:13], v[12:13], v[16:17]
	v_pk_add_f32 v[14:15], v[14:15], v[18:19]
	v_pk_add_f32 v[18:19], v[8:9], v[20:21]
	v_cvt_pk_bf16_f32 v8, v12, v13
	v_mul_f32_e32 v13, v13, v13
	v_fmac_f32_e32 v13, v12, v12
	v_mul_f32_e32 v12, v15, v15
	v_lshlrev_b32_e32 v24, 16, v64
	v_and_b32_e32 v25, 0xffff0000, v64
	v_lshlrev_b32_e32 v26, 16, v65
	v_and_b32_e32 v27, 0xffff0000, v65
	v_fmac_f32_e32 v12, v14, v14
	v_lshlrev_b32_e32 v22, 16, v71
	v_and_b32_e32 v23, 0xffff0000, v71
	v_lshlrev_b32_e32 v28, 16, v66
	v_and_b32_e32 v29, 0xffff0000, v66
	v_add_f32_e32 v12, v13, v12
	v_mul_f32_e32 v13, v19, v19
	v_pk_add_f32 v[6:7], v[6:7], v[26:27]
	v_pk_add_f32 v[4:5], v[4:5], v[24:25]
	v_pk_add_f32 v[16:17], v[10:11], v[22:23]
	v_cvt_pk_bf16_f32 v9, v14, v15
	v_fmac_f32_e32 v13, v18, v18
	v_pk_add_f32 v[14:15], v[0:1], v[28:29]
	v_mul_f32_e32 v0, v5, v5
	v_mul_f32_e32 v1, v7, v7
	v_add_f32_e32 v12, v13, v12
	v_mul_f32_e32 v13, v17, v17
	v_fmac_f32_e32 v0, v4, v4
	v_fmac_f32_e32 v1, v6, v6
	v_lshlrev_b32_e32 v30, 16, v67
	v_and_b32_e32 v31, 0xffff0000, v67
	v_fmac_f32_e32 v13, v16, v16
	v_add_f32_e32 v0, v0, v1
	v_mul_f32_e32 v1, v15, v15
	v_cvt_pk_bf16_f32 v10, v18, v19
	v_cvt_pk_bf16_f32 v11, v16, v17
	v_add_f32_e32 v16, v13, v12
	v_pk_add_f32 v[12:13], v[2:3], v[30:31]
	v_fmac_f32_e32 v1, v14, v14
	v_add_f32_e32 v0, v1, v0
	v_mul_f32_e32 v1, v13, v13
	v_fmac_f32_e32 v1, v12, v12
	v_add_f32_e32 v0, v1, v0
	v_add_f32_e32 v3, v16, v0
	ds_bpermute_b32 v18, v195, v3
	v_lshl_add_u64 v[0:1], s[12:13], 0, v[90:91]
	v_lshl_add_u64 v[16:17], v[170:171], 1, v[0:1]
	global_store_dwordx4 v[16:17], v[8:11], off
	v_cvt_pk_bf16_f32 v2, v4, v5
	s_waitcnt lgkmcnt(0)
	v_add_f32_e32 v0, v3, v18
	ds_bpermute_b32 v1, v112, v0
	v_cvt_pk_bf16_f32 v3, v6, v7
	v_cvt_pk_bf16_f32 v4, v14, v15
	v_cvt_pk_bf16_f32 v5, v12, v13
	global_store_dwordx4 v[16:17], v[2:5], off offset:256
	s_and_saveexec_b64 s[26:27], s[2:3]
	s_cbranch_execz .LBB0_1476
	v_lshl_add_u64 v[2:3], v[88:89], 2, s[6:7]
	s_waitcnt lgkmcnt(0)
	v_add_f32_e32 v0, v0, v1
	global_atomic_add_f32 v[2:3], v0, off
.LBB0_1476:
	s_or_b64 exec, exec, s[26:27]
	s_andn2_b64 vcc, exec, s[4:5]
	s_mov_b64 s[4:5], -1
	s_mov_b32 s101, 1
	s_cbranch_vccnz .LBB0_1449
	s_andn2_b64 vcc, exec, s[8:9]
	s_cbranch_vccnz .LBB0_1448
	s_barrier
	s_branch .LBB0_1448
.LBB0_1479:
	s_mov_b32 s101, 0
	s_waitcnt vmcnt(0)
	s_barrier
.LBB0_1480:
	v_readlane_b32 s0, v245, 11
	v_readlane_b32 s1, v245, 12
	s_mov_b64 s[2:3], -1
	s_and_b64 vcc, exec, s[0:1]
	s_cbranch_vccz .LBB0_1534
	s_waitcnt vmcnt(0)
	s_waitcnt lgkmcnt(0)
	s_barrier
	s_and_saveexec_b64 s[2:3], s[90:91]
	s_cbranch_execz .LBB0_1533
	s_add_i32 s0, 0, 0x23fc0
	v_mov_b32_e32 v0, s0
	s_waitcnt vmcnt(0) expcnt(0) lgkmcnt(0)
	ds_read_b32 v2, v0
	s_add_i32 s0, 0, 0x23fc4
	v_mov_b32_e32 v0, s0
	ds_read_b32 v0, v0
	s_waitcnt lgkmcnt(1)
	v_cmp_ne_u32_e32 vcc, 0, v2
	s_cbranch_vccnz .LBB0_1497
	s_add_u32 s4, s74, 0x1000
	s_addc_u32 s5, s75, 0
	s_add_u32 s8, s74, 0x1100
	s_addc_u32 s9, s75, 0
	s_add_u32 s10, s74, 0x1200
	s_addc_u32 s11, s75, 0
	s_mul_i32 s0, s77, s94
	s_add_u32 s12, s74, 0x1300
	s_mul_i32 s0, s0, s76
	s_addc_u32 s13, s75, 0
	s_mov_b32 s1, 1
	v_mov_b32_e32 v16, 0
	s_branch .LBB0_1485

;     __device__ __forceinline__ void operator()(Acc& acc, const Unit& u, int wr, int wc, int fr, int fq) const {
;     ...
;         const f32x4 g00 = *(const f32x4*)(gain + col0), g01 = *(const f32x4*)(gain + col0 + 4), g10 = *(const f32x4*)(gain + col0 + HALF), g11 = *(const f32x4*)(gain + col0 + HALF + 4);
; #pragma unroll
;         for (int ai = 0; ai < 2; ++ai)
; #pragma unroll
;             for (int m = 0; m < 4; ++m) {
;                 const int row = row0 + ai * HALF + m * 16;
;                 const float r = rsqrtf(__hip_atomic_load(ss + row, __ATOMIC_RELAXED, __HIP_MEMORY_SCOPE_AGENT) * (1.0f / DM) + NORM_EPS);
;                 float* op = out + (size_t)row * DM + col0;
;                 *(f32x4*)op = acc[ai][0][m][0] * r * g00; *(f32x4*)(op + 4) = acc[ai][0][m][1] * r * g01;
;                 *(f32x4*)(op + HALF) = acc[ai][1][m][0] * r * g10; *(f32x4*)(op + HALF + 4) = acc[ai][1][m][1] * r * g11;
.LBB0_1752:
	v_lshlrev_b64 v[80:81], 2, v[176:177]
	v_lshl_add_u64 v[8:9], s[86:87], 0, v[80:81]
	global_load_dwordx4 v[4:7], v[8:9], off offset:16
	global_load_dwordx4 v[12:15], v[8:9], off
	s_waitcnt lgkmcnt(0)
	global_load_dwordx4 v[0:3], v[8:9], off offset:528
	s_nop 0
	global_load_dwordx4 v[8:11], v[8:9], off offset:512
	global_load_dword v204, v[112:113], off sc1
	global_load_dword v205, v[188:189], off sc1
	global_load_dword v206, v[190:191], off sc1
	global_load_dword v207, v[192:193], off sc1
	global_load_dword v208, v[112:113], off offset:512 sc1
	global_load_dword v209, v[112:113], off offset:576 sc1
	global_load_dword v210, v[112:113], off offset:640 sc1
	global_load_dword v211, v[112:113], off offset:704 sc1
	s_nop 0
	s_waitcnt vmcnt(0)
	v_fmamk_f32 v82, v204, 0x3a800000, v203
	v_mul_f32_e32 v83, 0x4b800000, v82
	v_cmp_gt_f32_e32 vcc, s43, v82
	s_nop 1
	v_cndmask_b32_e32 v82, v82, v83, vcc
	v_rsq_f32_e32 v84, v82
	v_lshlrev_b64 v[82:83], 12, v[174:175]
	v_lshl_add_u64 v[82:83], s[72:73], 0, v[82:83]
	v_lshl_add_u64 v[86:87], v[82:83], 0, v[80:81]
	v_mul_f32_e32 v82, 0x45800000, v84
	v_cndmask_b32_e32 v82, v84, v82, vcc
	v_pk_mul_f32 v[174:175], v[178:179], v[82:83] op_sel_hi:[1,0]
	v_pk_mul_f32 v[84:85], v[126:127], v[82:83] op_sel_hi:[1,0]
	v_pk_mul_f32 v[124:125], v[124:125], v[82:83] op_sel_hi:[1,0]
	v_pk_mul_f32 v[122:123], v[122:123], v[82:83] op_sel_hi:[1,0]
	v_pk_mul_f32 v[126:127], v[120:121], v[82:83] op_sel_hi:[1,0]
	v_pk_mul_f32 v[118:119], v[118:119], v[82:83] op_sel_hi:[1,0]
	v_pk_mul_f32 v[176:177], v[116:117], v[82:83] op_sel_hi:[1,0]
	v_pk_mul_f32 v[178:179], v[114:115], v[82:83] op_sel_hi:[1,0]
	v_pk_mul_f32 v[84:85], v[14:15], v[84:85]
	v_pk_mul_f32 v[82:83], v[12:13], v[174:175]
	v_pk_mul_f32 v[116:117], v[6:7], v[122:123]
	v_pk_mul_f32 v[114:115], v[4:5], v[124:125]
	v_pk_mul_f32 v[120:121], v[10:11], v[118:119]
	v_pk_mul_f32 v[118:119], v[8:9], v[126:127]
	v_pk_mul_f32 v[124:125], v[2:3], v[178:179]
	v_pk_mul_f32 v[122:123], v[0:1], v[176:177]
	global_store_dwordx4 v[86:87], v[82:85], off
	global_store_dwordx4 v[86:87], v[114:117], off offset:16
	global_store_dwordx4 v[86:87], v[118:121], off offset:512
	global_store_dwordx4 v[86:87], v[122:125], off offset:528
	s_nop 1
	v_fmamk_f32 v82, v205, 0x3a800000, v203
	v_mul_f32_e32 v83, 0x4b800000, v82
	v_cmp_gt_f32_e32 vcc, s43, v82
	s_nop 1
	v_cndmask_b32_e32 v82, v82, v83, vcc
	v_rsq_f32_e32 v84, v82
	v_lshlrev_b64 v[82:83], 12, v[172:173]
	v_lshl_add_u64 v[82:83], s[72:73], 0, v[82:83]
	v_lshl_add_u64 v[86:87], v[82:83], 0, v[80:81]
	v_mul_f32_e32 v82, 0x45800000, v84
	v_cndmask_b32_e32 v82, v84, v82, vcc
	v_pk_mul_f32 v[108:109], v[108:109], v[82:83] op_sel_hi:[1,0]
	v_pk_mul_f32 v[84:85], v[110:111], v[82:83] op_sel_hi:[1,0]
	v_pk_mul_f32 v[104:105], v[104:105], v[82:83] op_sel_hi:[1,0]
	v_pk_mul_f32 v[106:107], v[106:107], v[82:83] op_sel_hi:[1,0]
	v_pk_mul_f32 v[100:101], v[100:101], v[82:83] op_sel_hi:[1,0]
	v_pk_mul_f32 v[102:103], v[102:103], v[82:83] op_sel_hi:[1,0]
	v_pk_mul_f32 v[110:111], v[96:97], v[82:83] op_sel_hi:[1,0]
	v_pk_mul_f32 v[114:115], v[98:99], v[82:83] op_sel_hi:[1,0]
	v_pk_mul_f32 v[84:85], v[14:15], v[84:85]
	v_pk_mul_f32 v[82:83], v[12:13], v[108:109]
	v_pk_mul_f32 v[98:99], v[6:7], v[106:107]
	v_pk_mul_f32 v[96:97], v[4:5], v[104:105]
	v_pk_mul_f32 v[102:103], v[10:11], v[102:103]
	v_pk_mul_f32 v[100:101], v[8:9], v[100:101]
	v_pk_mul_f32 v[106:107], v[2:3], v[114:115]
	v_pk_mul_f32 v[104:105], v[0:1], v[110:111]
	global_store_dwordx4 v[86:87], v[82:85], off
	global_store_dwordx4 v[86:87], v[96:99], off offset:16
	global_store_dwordx4 v[86:87], v[100:103], off offset:512
	global_store_dwordx4 v[86:87], v[104:107], off offset:528
	s_nop 1
	v_fmamk_f32 v82, v206, 0x3a800000, v203
	v_mul_f32_e32 v83, 0x4b800000, v82
	v_cmp_gt_f32_e32 vcc, s43, v82
	s_nop 1
	v_cndmask_b32_e32 v82, v82, v83, vcc
	v_rsq_f32_e32 v84, v82
	v_lshlrev_b64 v[82:83], 12, v[170:171]
	v_lshl_add_u64 v[82:83], s[72:73], 0, v[82:83]
	v_lshl_add_u64 v[86:87], v[82:83], 0, v[80:81]
	v_mul_f32_e32 v82, 0x45800000, v84
	v_cndmask_b32_e32 v82, v84, v82, vcc
	v_pk_mul_f32 v[96:97], v[144:145], v[82:83] op_sel_hi:[1,0]
	v_pk_mul_f32 v[84:85], v[94:95], v[82:83] op_sel_hi:[1,0]
	v_pk_mul_f32 v[94:95], v[142:143], v[82:83] op_sel_hi:[1,0]
	v_pk_mul_f32 v[98:99], v[140:141], v[82:83] op_sel_hi:[1,0]
	v_pk_mul_f32 v[102:103], v[146:147], v[82:83] op_sel_hi:[1,0]
	v_pk_mul_f32 v[100:101], v[136:137], v[82:83] op_sel_hi:[1,0]
	v_pk_mul_f32 v[106:107], v[148:149], v[82:83] op_sel_hi:[1,0]
	v_pk_mul_f32 v[104:105], v[138:139], v[82:83] op_sel_hi:[1,0]
	v_pk_mul_f32 v[84:85], v[14:15], v[84:85]
	v_pk_mul_f32 v[82:83], v[12:13], v[96:97]
	v_pk_mul_f32 v[96:97], v[6:7], v[98:99]
	v_pk_mul_f32 v[94:95], v[4:5], v[94:95]
	v_pk_mul_f32 v[100:101], v[10:11], v[100:101]
	v_pk_mul_f32 v[98:99], v[8:9], v[102:103]
	v_pk_mul_f32 v[104:105], v[2:3], v[104:105]
	v_pk_mul_f32 v[102:103], v[0:1], v[106:107]
	global_store_dwordx4 v[86:87], v[82:85], off
	global_store_dwordx4 v[86:87], v[94:97], off offset:16
	global_store_dwordx4 v[86:87], v[98:101], off offset:512
	global_store_dwordx4 v[86:87], v[102:105], off offset:528
	s_nop 1
	v_fmamk_f32 v82, v207, 0x3a800000, v203
	v_mul_f32_e32 v83, 0x4b800000, v82
	v_cmp_gt_f32_e32 vcc, s43, v82
	s_nop 1
	v_cndmask_b32_e32 v82, v82, v83, vcc
	v_rsq_f32_e32 v84, v82
	v_lshlrev_b64 v[82:83], 12, v[168:169]
	v_lshl_add_u64 v[82:83], s[72:73], 0, v[82:83]
	v_lshl_add_u64 v[86:87], v[82:83], 0, v[80:81]
	v_mul_f32_e32 v82, 0x45800000, v84
	v_cndmask_b32_e32 v82, v84, v82, vcc
	v_pk_mul_f32 v[94:95], v[150:151], v[82:83] op_sel_hi:[1,0]
;     __device__ __forceinline__ void operator()(Acc& acc, const Unit& u, int wr, int wc, int fr, int fq) const {
;     ...
; #pragma unroll
;         for (int ai = 0; ai < 2; ++ai)
; #pragma unroll
;             for (int m = 0; m < 4; ++m) {
;                 const int row = row0 + ai * HALF + m * 16;
;                 const float r = rsqrtf(__hip_atomic_load(ss + row, __ATOMIC_RELAXED, __HIP_MEMORY_SCOPE_AGENT) * (1.0f / DM) + NORM_EPS);
;                 float* op = out + (size_t)row * DM + col0;
;                 *(f32x4*)op = acc[ai][0][m][0] * r * g00; *(f32x4*)(op + 4) = acc[ai][0][m][1] * r * g01;
;                 *(f32x4*)(op + HALF) = acc[ai][1][m][0] * r * g10; *(f32x4*)(op + HALF + 4) = acc[ai][1][m][1] * r * g11;
;             }
	v_pk_mul_f32 v[84:85], v[132:133], v[82:83] op_sel_hi:[1,0]
	v_pk_mul_f32 v[98:99], v[180:181], v[82:83] op_sel_hi:[1,0]
	v_pk_mul_f32 v[96:97], v[134:135], v[82:83] op_sel_hi:[1,0]
	v_pk_mul_f32 v[102:103], v[182:183], v[82:83] op_sel_hi:[1,0]
	v_pk_mul_f32 v[100:101], v[128:129], v[82:83] op_sel_hi:[1,0]
	v_pk_mul_f32 v[106:107], v[184:185], v[82:83] op_sel_hi:[1,0]
	v_pk_mul_f32 v[104:105], v[130:131], v[82:83] op_sel_hi:[1,0]
	v_pk_mul_f32 v[84:85], v[14:15], v[84:85]
	v_pk_mul_f32 v[82:83], v[12:13], v[94:95]
	v_pk_mul_f32 v[96:97], v[6:7], v[96:97]
	v_pk_mul_f32 v[94:95], v[4:5], v[98:99]
	v_pk_mul_f32 v[100:101], v[10:11], v[100:101]
	v_pk_mul_f32 v[98:99], v[8:9], v[102:103]
	v_pk_mul_f32 v[104:105], v[2:3], v[104:105]
	v_pk_mul_f32 v[102:103], v[0:1], v[106:107]
	global_store_dwordx4 v[86:87], v[82:85], off
	global_store_dwordx4 v[86:87], v[94:97], off offset:16
	global_store_dwordx4 v[86:87], v[98:101], off offset:512
	global_store_dwordx4 v[86:87], v[102:105], off offset:528
	s_nop 1
	v_fmamk_f32 v82, v208, 0x3a800000, v203
	v_mul_f32_e32 v83, 0x4b800000, v82
	v_cmp_gt_f32_e32 vcc, s43, v82
	s_nop 1
	v_cndmask_b32_e32 v82, v82, v83, vcc
	v_rsq_f32_e32 v84, v82
	v_lshlrev_b64 v[82:83], 12, v[186:187]
	v_lshl_add_u64 v[82:83], s[72:73], 0, v[82:83]
	v_lshl_add_u64 v[82:83], v[82:83], 0, v[80:81]
	v_mul_f32_e32 v85, 0x45800000, v84
	v_cndmask_b32_e32 v84, v84, v85, vcc
	v_pk_mul_f32 v[60:61], v[60:61], v[84:85] op_sel_hi:[1,0]
	v_pk_mul_f32 v[62:63], v[62:63], v[84:85] op_sel_hi:[1,0]
	v_pk_mul_f32 v[56:57], v[56:57], v[84:85] op_sel_hi:[1,0]
	v_pk_mul_f32 v[58:59], v[58:59], v[84:85] op_sel_hi:[1,0]
	v_pk_mul_f32 v[86:87], v[52:53], v[84:85] op_sel_hi:[1,0]
	v_pk_mul_f32 v[94:95], v[54:55], v[84:85] op_sel_hi:[1,0]
	v_pk_mul_f32 v[96:97], v[48:49], v[84:85] op_sel_hi:[1,0]
	v_pk_mul_f32 v[84:85], v[50:51], v[84:85] op_sel_hi:[1,0]
	v_pk_mul_f32 v[50:51], v[14:15], v[62:63]
	v_pk_mul_f32 v[48:49], v[12:13], v[60:61]
	v_pk_mul_f32 v[54:55], v[6:7], v[58:59]
	v_pk_mul_f32 v[52:53], v[4:5], v[56:57]
	v_pk_mul_f32 v[58:59], v[10:11], v[94:95]
	v_pk_mul_f32 v[56:57], v[8:9], v[86:87]
	v_pk_mul_f32 v[62:63], v[2:3], v[84:85]
	v_pk_mul_f32 v[60:61], v[0:1], v[96:97]
	global_store_dwordx4 v[82:83], v[48:51], off
	global_store_dwordx4 v[82:83], v[52:55], off offset:16
	global_store_dwordx4 v[82:83], v[56:59], off offset:512
	global_store_dwordx4 v[82:83], v[60:63], off offset:528
	s_nop 1
	v_fmamk_f32 v48, v209, 0x3a800000, v203
	v_mul_f32_e32 v49, 0x4b800000, v48
	v_cmp_gt_f32_e32 vcc, s43, v48
	s_nop 1
	v_cndmask_b32_e32 v48, v48, v49, vcc
	v_rsq_f32_e32 v50, v48
	v_lshlrev_b64 v[48:49], 12, v[92:93]
	v_lshl_add_u64 v[48:49], s[72:73], 0, v[48:49]
	v_lshl_add_u64 v[48:49], v[48:49], 0, v[80:81]
	v_mul_f32_e32 v51, 0x45800000, v50
	v_cndmask_b32_e32 v50, v50, v51, vcc
	v_pk_mul_f32 v[44:45], v[44:45], v[50:51] op_sel_hi:[1,0]
	v_pk_mul_f32 v[46:47], v[46:47], v[50:51] op_sel_hi:[1,0]
	v_pk_mul_f32 v[40:41], v[40:41], v[50:51] op_sel_hi:[1,0]
	v_pk_mul_f32 v[42:43], v[42:43], v[50:51] op_sel_hi:[1,0]
	v_pk_mul_f32 v[52:53], v[36:37], v[50:51] op_sel_hi:[1,0]
	v_pk_mul_f32 v[54:55], v[38:39], v[50:51] op_sel_hi:[1,0]
	v_pk_mul_f32 v[56:57], v[32:33], v[50:51] op_sel_hi:[1,0]
	v_pk_mul_f32 v[50:51], v[34:35], v[50:51] op_sel_hi:[1,0]
	v_pk_mul_f32 v[34:35], v[14:15], v[46:47]
	v_pk_mul_f32 v[32:33], v[12:13], v[44:45]
	v_pk_mul_f32 v[38:39], v[6:7], v[42:43]
	v_pk_mul_f32 v[36:37], v[4:5], v[40:41]
	v_pk_mul_f32 v[42:43], v[10:11], v[54:55]
	v_pk_mul_f32 v[40:41], v[8:9], v[52:53]
	v_pk_mul_f32 v[46:47], v[2:3], v[50:51]
	v_pk_mul_f32 v[44:45], v[0:1], v[56:57]
	global_store_dwordx4 v[48:49], v[32:35], off
	global_store_dwordx4 v[48:49], v[36:39], off offset:16
	global_store_dwordx4 v[48:49], v[40:43], off offset:512
	global_store_dwordx4 v[48:49], v[44:47], off offset:528
	s_nop 1
	v_fmamk_f32 v32, v210, 0x3a800000, v203
	v_mul_f32_e32 v33, 0x4b800000, v32
	v_cmp_gt_f32_e32 vcc, s43, v32
	s_nop 1
	v_cndmask_b32_e32 v32, v32, v33, vcc
	v_rsq_f32_e32 v34, v32
	v_lshlrev_b64 v[32:33], 12, v[90:91]
	v_lshl_add_u64 v[32:33], s[72:73], 0, v[32:33]
	v_lshl_add_u64 v[40:41], v[32:33], 0, v[80:81]
	v_mul_f32_e32 v32, 0x45800000, v34
	v_cndmask_b32_e32 v32, v34, v32, vcc
	v_pk_mul_f32 v[28:29], v[28:29], v[32:33] op_sel_hi:[1,0]
	v_pk_mul_f32 v[30:31], v[30:31], v[32:33] op_sel_hi:[1,0]
	v_pk_mul_f32 v[34:35], v[24:25], v[32:33] op_sel_hi:[1,0]
	v_pk_mul_f32 v[36:37], v[26:27], v[32:33] op_sel_hi:[1,0]
	v_pk_mul_f32 v[38:39], v[76:77], v[32:33] op_sel_hi:[1,0]
	v_pk_mul_f32 v[42:43], v[72:73], v[32:33] op_sel_hi:[1,0]
	v_pk_mul_f32 v[44:45], v[78:79], v[32:33] op_sel_hi:[1,0]
	v_pk_mul_f32 v[46:47], v[74:75], v[32:33] op_sel_hi:[1,0]
	v_pk_mul_f32 v[26:27], v[14:15], v[30:31]
	v_pk_mul_f32 v[24:25], v[12:13], v[28:29]
	v_pk_mul_f32 v[30:31], v[6:7], v[36:37]
	v_pk_mul_f32 v[28:29], v[4:5], v[34:35]
	v_pk_mul_f32 v[34:35], v[10:11], v[42:43]
	v_pk_mul_f32 v[32:33], v[8:9], v[38:39]
	v_pk_mul_f32 v[38:39], v[2:3], v[46:47]
	v_pk_mul_f32 v[36:37], v[0:1], v[44:45]
	global_store_dwordx4 v[40:41], v[24:27], off
	global_store_dwordx4 v[40:41], v[28:31], off offset:16
	global_store_dwordx4 v[40:41], v[32:35], off offset:512
	global_store_dwordx4 v[40:41], v[36:39], off offset:528
	v_lshlrev_b64 v[24:25], 12, v[88:89]
	v_lshl_add_u64 v[24:25], s[72:73], 0, v[24:25]
	s_and_b64 vcc, exec, s[4:5]
	v_lshl_add_u64 v[24:25], v[24:25], 0, v[80:81]
	s_mov_b64 s[4:5], -1
	s_nop 1
	v_fmamk_f32 v26, v211, 0x3a800000, v203
	v_mul_f32_e32 v27, 0x4b800000, v26
	v_cmp_gt_f32_e64 s[6:7], s43, v26
	s_nop 1
	v_cndmask_b32_e64 v26, v26, v27, s[6:7]
	v_rsq_f32_e32 v26, v26
	s_nop 0
	v_mul_f32_e32 v27, 0x45800000, v26
	v_cndmask_b32_e64 v26, v26, v27, s[6:7]
	v_pk_mul_f32 v[18:19], v[18:19], v[26:27] op_sel_hi:[1,0]
	v_pk_mul_f32 v[16:17], v[16:17], v[26:27] op_sel_hi:[1,0]
	v_pk_mul_f32 v[22:23], v[22:23], v[26:27] op_sel_hi:[1,0]
	v_pk_mul_f32 v[20:21], v[20:21], v[26:27] op_sel_hi:[1,0]
	v_pk_mul_f32 v[28:29], v[68:69], v[26:27] op_sel_hi:[1,0]
	v_pk_mul_f32 v[30:31], v[64:65], v[26:27] op_sel_hi:[1,0]
	v_pk_mul_f32 v[32:33], v[70:71], v[26:27] op_sel_hi:[1,0]
	v_pk_mul_f32 v[26:27], v[66:67], v[26:27] op_sel_hi:[1,0]
	v_pk_mul_f32 v[14:15], v[14:15], v[16:17]
	v_pk_mul_f32 v[12:13], v[12:13], v[18:19]
	v_pk_mul_f32 v[6:7], v[6:7], v[20:21]
	v_pk_mul_f32 v[4:5], v[4:5], v[22:23]
	v_pk_mul_f32 v[10:11], v[10:11], v[30:31]
	v_pk_mul_f32 v[8:9], v[8:9], v[28:29]
	v_pk_mul_f32 v[2:3], v[2:3], v[26:27]
	v_pk_mul_f32 v[0:1], v[0:1], v[32:33]
	global_store_dwordx4 v[24:25], v[12:15], off
	global_store_dwordx4 v[24:25], v[4:7], off offset:16
	global_store_dwordx4 v[24:25], v[8:11], off offset:512
	global_store_dwordx4 v[24:25], v[0:3], off offset:528
	s_cbranch_vccnz .LBB0_1710
	s_andn2_b64 vcc, exec, s[8:9]
	s_cbranch_vccnz .LBB0_1709
	s_barrier
	s_branch .LBB0_1709

; __global__ void __launch_bounds__(NWAVES * 64, 2) fwd_megakernel(Args args) {
	.amdhsa_kernel _Z14fwd_megakernel4Args
		.amdhsa_group_segment_fixed_size 0
		.amdhsa_private_segment_fixed_size 0
		.amdhsa_kernarg_size 440
		.amdhsa_user_sgpr_count 2
		.amdhsa_user_sgpr_dispatch_ptr 0
		.amdhsa_user_sgpr_queue_ptr 0
		.amdhsa_user_sgpr_kernarg_segment_ptr 1
		.amdhsa_user_sgpr_dispatch_id 0
		.amdhsa_user_sgpr_kernarg_preload_length 0
		.amdhsa_user_sgpr_kernarg_preload_offset 0
		.amdhsa_user_sgpr_private_segment_size 0
		.amdhsa_uses_dynamic_stack 0
		.amdhsa_enable_private_segment 0
		.amdhsa_system_sgpr_workgroup_id_x 1
		.amdhsa_system_sgpr_workgroup_id_y 0
		.amdhsa_system_sgpr_workgroup_id_z 0
		.amdhsa_system_sgpr_workgroup_info 0
		.amdhsa_system_vgpr_workitem_id 2
		.amdhsa_next_free_vgpr 256
		.amdhsa_next_free_sgpr 102
		.amdhsa_accum_offset 256
		.amdhsa_reserve_vcc 1
		.amdhsa_float_round_mode_32 0
		.amdhsa_float_round_mode_16_64 0
		.amdhsa_float_denorm_mode_32 3
		.amdhsa_float_denorm_mode_16_64 3
		.amdhsa_dx10_clamp 1
		.amdhsa_ieee_mode 1
		.amdhsa_fp16_overflow 0
		.amdhsa_tg_split 0
		.amdhsa_exception_fp_ieee_invalid_op 0
		.amdhsa_exception_fp_denorm_src 0
		.amdhsa_exception_fp_ieee_div_zero 0
		.amdhsa_exception_fp_ieee_overflow 0
		.amdhsa_exception_fp_ieee_underflow 0
		.amdhsa_exception_fp_ieee_inexact 0
		.amdhsa_exception_int_div_zero 0
	.end_amdhsa_kernel

; __global__ void __launch_bounds__(NWAVES * 64, 2) fwd_megakernel(Args args) {
amdhsa.kernels:
  - .agpr_count:     0
    .args:
      - .offset:         0
        .size:           184
        .value_kind:     by_value
      - .offset:         184
        .size:           4
        .value_kind:     hidden_block_count_x
      - .offset:         188
        .size:           4
        .value_kind:     hidden_block_count_y
      - .offset:         192
        .size:           4
        .value_kind:     hidden_block_count_z
      - .offset:         196
        .size:           2
        .value_kind:     hidden_group_size_x
      - .offset:         198
        .size:           2
        .value_kind:     hidden_group_size_y
      - .offset:         200
        .size:           2
        .value_kind:     hidden_group_size_z
      - .offset:         202
        .size:           2
        .value_kind:     hidden_remainder_x
      - .offset:         204
        .size:           2
        .value_kind:     hidden_remainder_y
      - .offset:         206
        .size:           2
        .value_kind:     hidden_remainder_z
      - .offset:         224
        .size:           8
        .value_kind:     hidden_global_offset_x
      - .offset:         232
        .size:           8
        .value_kind:     hidden_global_offset_y
      - .offset:         240
        .size:           8
        .value_kind:     hidden_global_offset_z
      - .offset:         248
        .size:           2
        .value_kind:     hidden_grid_dims
      - .offset:         272
        .size:           8
        .value_kind:     hidden_multigrid_sync_arg
      - .offset:         304
        .size:           4
        .value_kind:     hidden_dynamic_lds_size
    .group_segment_fixed_size: 0
    .kernarg_segment_align: 8
    .kernarg_segment_size: 440
    .language:       OpenCL C
    .language_version:
      - 2
      - 0
    .max_flat_workgroup_size: 512
    .name:           _Z14fwd_megakernel4Args
    .private_segment_fixed_size: 0
    .sgpr_count:     108
    .sgpr_spill_count: 25
    .symbol:         _Z14fwd_megakernel4Args.kd
    .uniform_work_group_size: 1
    .uses_dynamic_stack: false
    .vgpr_count:     256
    .vgpr_spill_count: 0
    .wavefront_size: 64
